# epiresid_stores_sc1_nt_too
# baseline (speedup 1.0000x reference)
.LBB0_887:
	v_lshl_add_u32 v182, s26, 8, v169
	v_lshl_or_b32 v180, s51, 8, v192
	v_ashrrev_i32_e32 v183, 31, v182
	v_ashrrev_i32_e32 v181, 31, v180
	v_lshl_add_u64 v[184:185], v[180:181], 2, s[4:5]
	v_lshlrev_b64 v[128:129], 12, v[182:183]
	v_lshl_add_u64 v[128:129], v[184:185], 0, v[128:129]
	global_load_dwordx4 v[198:201], v[128:129], off offset:528
	global_load_dwordx4 v[202:205], v[128:129], off offset:512
	v_lshlrev_b64 v[128:129], 10, v[182:183]
	v_lshl_add_u64 v[188:189], v[128:129], 0, v[180:181]
	v_lshl_add_u64 v[128:129], v[188:189], 2, s[4:5]
	global_load_dwordx4 v[206:209], v[128:129], off
	global_load_dwordx4 v[210:213], v[128:129], off offset:16
	v_or_b32_e32 v190, 16, v182
	v_or_b32_e32 v186, 32, v182
	v_ashrrev_i32_e32 v191, 31, v190
	v_ashrrev_i32_e32 v187, 31, v186
	v_lshlrev_b64 v[128:129], 12, v[190:191]
	v_lshlrev_b64 v[130:131], 12, v[186:187]
	v_lshl_add_u64 v[128:129], v[184:185], 0, v[128:129]
	v_lshl_add_u64 v[132:133], v[184:185], 0, v[130:131]
	global_load_dwordx4 v[152:155], v[128:129], off offset:16
	global_load_dwordx4 v[156:159], v[128:129], off
	global_load_dwordx4 v[144:147], v[128:129], off offset:528
	global_load_dwordx4 v[148:151], v[128:129], off offset:512
	global_load_dwordx4 v[136:139], v[132:133], off offset:16
	global_load_dwordx4 v[140:143], v[132:133], off
	s_nop 0
	global_load_dwordx4 v[128:131], v[132:133], off offset:528
	s_nop 0
	global_load_dwordx4 v[132:135], v[132:133], off offset:512
	v_and_b32_e32 v214, 64, v196
	v_xor_b32_e32 v197, 16, v196
	v_add_u32_e32 v214, 64, v214
	v_cmp_lt_i32_e32 vcc, v197, v214
	v_xor_b32_e32 v215, 32, v196
	v_lshl_add_u64 v[188:189], v[188:189], 1, s[12:13]
	v_cndmask_b32_e32 v197, v196, v197, vcc
	v_lshlrev_b32_e32 v197, 2, v197
	v_cmp_lt_i32_e32 vcc, v215, v214
	s_waitcnt vmcnt(8)
	v_pk_add_f32 v[200:201], v[114:115], v[200:201]
	v_pk_add_f32 v[204:205], v[118:119], v[204:205]
	v_pk_add_f32 v[202:203], v[116:117], v[202:203]
	v_pk_add_f32 v[112:113], v[112:113], v[198:199]
	v_pk_add_f32 v[126:127], v[126:127], v[208:209]
	v_pk_add_f32 v[124:125], v[124:125], v[206:207]
	v_pk_add_f32 v[122:123], v[122:123], v[212:213]
	v_pk_add_f32 v[120:121], v[120:121], v[210:211]
	v_mul_f32_e32 v119, v203, v203
	v_mul_f32_e32 v198, v205, v205
	v_mul_f32_e32 v199, v113, v113
	v_mul_f32_e32 v206, v201, v201
	v_cvt_pk_bf16_f32 v114, v202, v203
	v_cvt_pk_bf16_f32 v115, v204, v205
	v_cvt_pk_bf16_f32 v116, v112, v113
	v_cvt_pk_bf16_f32 v117, v200, v201
	v_mul_f32_e32 v113, v125, v125
	v_mul_f32_e32 v201, v127, v127
	v_mul_f32_e32 v203, v121, v121
	v_mul_f32_e32 v205, v123, v123
	v_fmac_f32_e32 v119, v202, v202
	v_fmac_f32_e32 v198, v204, v204
	v_fmac_f32_e32 v199, v112, v112
	v_fmac_f32_e32 v206, v200, v200
	v_fmac_f32_e32 v113, v124, v124
	v_fmac_f32_e32 v201, v126, v126
	v_fmac_f32_e32 v203, v120, v120
	v_fmac_f32_e32 v205, v122, v122
	v_cvt_pk_bf16_f32 v118, v124, v125
	v_add_f32_e32 v112, v119, v198
	v_add_f32_e32 v119, v199, v206
	v_add_f32_e32 v113, v113, v201
	v_add_f32_e32 v124, v203, v205
	v_add_f32_e32 v112, v112, v119
	v_add_f32_e32 v113, v113, v124
	v_add_f32_e32 v112, v113, v112
	ds_bpermute_b32 v113, v197, v112
	v_cndmask_b32_e32 v216, v196, v215, vcc
	v_lshlrev_b32_e32 v198, 2, v216
	v_cvt_pk_bf16_f32 v119, v126, v127
	v_cvt_pk_bf16_f32 v120, v120, v121
	s_waitcnt lgkmcnt(0)
	v_add_f32_e32 v112, v112, v113
	ds_bpermute_b32 v113, v198, v112
	v_cvt_pk_bf16_f32 v121, v122, v123
	global_store_dwordx4 v[188:189], v[118:121], off sc1 nt
	s_nop 1
	v_lshl_add_u64 v[214:215], v[188:189], 0, s[14:15]
	global_store_dwordx4 v[214:215], v[114:117], off sc1 nt
	s_nop 1
	s_and_saveexec_b64 s[0:1], s[6:7]
	s_cbranch_execz .LBB0_889
	s_waitcnt lgkmcnt(0)
	v_add_f32_e32 v114, v112, v113
	s_lshl_b32 s26, s51, 2
	v_lshlrev_b64 v[112:113], 6, v[182:183]
	s_ashr_i32 s27, s26, 31
	v_lshl_add_u64 v[112:113], s[18:19], 0, v[112:113]
	v_lshl_add_u64 v[112:113], s[26:27], 2, v[112:113]
	s_lshl_b32 s10, s45, 2
	v_lshl_add_u64 v[112:113], v[112:113], 0, s[10:11]
	global_store_dword v[112:113], v114, off
.LBB0_889:
	s_or_b64 exec, exec, s[0:1]
	v_or_b32_e32 v188, 48, v182
	v_ashrrev_i32_e32 v189, 31, v188
	s_waitcnt lgkmcnt(0)
	v_lshlrev_b64 v[112:113], 12, v[188:189]
	v_lshl_add_u64 v[116:117], v[184:185], 0, v[112:113]
	global_load_dwordx4 v[120:123], v[116:117], off offset:16
	global_load_dwordx4 v[124:127], v[116:117], off
	global_load_dwordx4 v[112:115], v[116:117], off offset:528
	s_nop 0
	global_load_dwordx4 v[116:119], v[116:117], off offset:512
	s_waitcnt vmcnt(11)
	v_pk_add_f32 v[110:111], v[110:111], v[158:159]
	v_pk_add_f32 v[108:109], v[108:109], v[156:157]
	v_pk_add_f32 v[154:155], v[106:107], v[154:155]
	v_pk_add_f32 v[106:107], v[104:105], v[152:153]
	v_mul_f32_e32 v104, v109, v109
	v_mul_f32_e32 v105, v111, v111
	v_fmac_f32_e32 v104, v108, v108
	v_fmac_f32_e32 v105, v110, v110
	v_add_f32_e32 v104, v104, v105
	v_mul_f32_e32 v105, v107, v107
	v_mul_f32_e32 v152, v155, v155
	v_fmac_f32_e32 v105, v106, v106
	v_fmac_f32_e32 v152, v154, v154
	v_lshlrev_b64 v[200:201], 10, v[190:191]
	v_add_f32_e32 v105, v105, v152
	v_lshl_add_u64 v[200:201], v[200:201], 0, v[180:181]
	v_add_f32_e32 v152, v104, v105
	v_cvt_pk_bf16_f32 v104, v108, v109
	v_cvt_pk_bf16_f32 v105, v110, v111
	v_pk_add_f32 v[102:103], v[102:103], v[150:151]
	v_pk_add_f32 v[100:101], v[100:101], v[148:149]
	v_cvt_pk_bf16_f32 v106, v106, v107
	v_cvt_pk_bf16_f32 v107, v154, v155
	v_lshl_add_u64 v[108:109], v[200:201], 1, s[12:13]
	global_store_dwordx4 v[108:109], v[104:107], off sc1 nt
	s_nop 1
	v_pk_add_f32 v[104:105], v[98:99], v[146:147]
	v_mul_f32_e32 v98, v101, v101
	v_mul_f32_e32 v99, v103, v103
	v_pk_add_f32 v[96:97], v[96:97], v[144:145]
	v_fmac_f32_e32 v98, v100, v100
	v_fmac_f32_e32 v99, v102, v102
	v_add_f32_e32 v98, v98, v99
	v_mul_f32_e32 v99, v97, v97
	v_mul_f32_e32 v106, v105, v105
	v_fmac_f32_e32 v99, v96, v96
	v_fmac_f32_e32 v106, v104, v104
	v_add_f32_e32 v99, v99, v106
	v_add_f32_e32 v98, v98, v99
	v_add_f32_e32 v106, v152, v98
	ds_bpermute_b32 v107, v197, v106
	v_cvt_pk_bf16_f32 v98, v100, v101
	v_cvt_pk_bf16_f32 v100, v96, v97
	v_cvt_pk_bf16_f32 v99, v102, v103
	v_cvt_pk_bf16_f32 v101, v104, v105
	s_waitcnt lgkmcnt(0)
	v_add_f32_e32 v96, v106, v107
	ds_bpermute_b32 v97, v198, v96
	v_lshl_add_u64 v[102:103], v[108:109], 0, s[14:15]
	global_store_dwordx4 v[102:103], v[98:101], off sc1 nt
	s_nop 1
	s_and_saveexec_b64 s[0:1], s[6:7]
	s_cbranch_execz .LBB0_891
	s_waitcnt lgkmcnt(0)
	v_add_f32_e32 v98, v96, v97
	s_lshl_b32 s26, s51, 2
	v_lshlrev_b64 v[96:97], 6, v[190:191]
	s_ashr_i32 s27, s26, 31
	v_lshl_add_u64 v[96:97], s[18:19], 0, v[96:97]
	v_lshl_add_u64 v[96:97], s[26:27], 2, v[96:97]
	s_lshl_b32 s10, s45, 2
	v_lshl_add_u64 v[96:97], v[96:97], 0, s[10:11]
	global_store_dword v[96:97], v98, off
.LBB0_891:
	s_or_b64 exec, exec, s[0:1]
	v_add_u32_e32 v144, 0x80, v182
	v_ashrrev_i32_e32 v145, 31, v144
	s_waitcnt lgkmcnt(0)
	v_lshlrev_b64 v[96:97], 12, v[144:145]
	v_lshl_add_u64 v[100:101], v[184:185], 0, v[96:97]
	global_load_dwordx4 v[104:107], v[100:101], off offset:16
	global_load_dwordx4 v[108:111], v[100:101], off
	global_load_dwordx4 v[96:99], v[100:101], off offset:528
	s_nop 0
	global_load_dwordx4 v[100:103], v[100:101], off offset:512
	s_waitcnt vmcnt(14)
	v_pk_add_f32 v[94:95], v[94:95], v[142:143]
	v_pk_add_f32 v[92:93], v[92:93], v[140:141]
	v_pk_add_f32 v[138:139], v[90:91], v[138:139]
	v_pk_add_f32 v[90:91], v[88:89], v[136:137]
	v_mul_f32_e32 v88, v93, v93
	v_mul_f32_e32 v89, v95, v95
	v_fmac_f32_e32 v88, v92, v92
	v_fmac_f32_e32 v89, v94, v94
	v_add_f32_e32 v88, v88, v89
	v_mul_f32_e32 v89, v91, v91
	v_mul_f32_e32 v136, v139, v139
	v_fmac_f32_e32 v89, v90, v90
	v_fmac_f32_e32 v136, v138, v138
	v_lshlrev_b64 v[146:147], 10, v[186:187]
	v_add_f32_e32 v89, v89, v136
	v_lshl_add_u64 v[146:147], v[146:147], 0, v[180:181]
	v_add_f32_e32 v136, v88, v89
	v_cvt_pk_bf16_f32 v88, v92, v93
	v_cvt_pk_bf16_f32 v89, v94, v95
	v_pk_add_f32 v[86:87], v[86:87], v[134:135]
	v_pk_add_f32 v[84:85], v[84:85], v[132:133]
	v_cvt_pk_bf16_f32 v90, v90, v91
	v_cvt_pk_bf16_f32 v91, v138, v139
	v_lshl_add_u64 v[92:93], v[146:147], 1, s[12:13]
	global_store_dwordx4 v[92:93], v[88:91], off sc1 nt
	s_nop 1
	v_pk_add_f32 v[88:89], v[82:83], v[130:131]
	v_mul_f32_e32 v82, v85, v85
	v_mul_f32_e32 v83, v87, v87
	v_pk_add_f32 v[80:81], v[80:81], v[128:129]
	v_fmac_f32_e32 v82, v84, v84
	v_fmac_f32_e32 v83, v86, v86
	v_add_f32_e32 v82, v82, v83
	v_mul_f32_e32 v83, v81, v81
	v_mul_f32_e32 v90, v89, v89
	v_fmac_f32_e32 v83, v80, v80
	v_fmac_f32_e32 v90, v88, v88
	v_add_f32_e32 v83, v83, v90
	v_add_f32_e32 v82, v82, v83
	v_add_f32_e32 v90, v136, v82
	ds_bpermute_b32 v91, v197, v90
	v_cvt_pk_bf16_f32 v82, v84, v85
	v_cvt_pk_bf16_f32 v84, v80, v81
	v_cvt_pk_bf16_f32 v83, v86, v87
	v_cvt_pk_bf16_f32 v85, v88, v89
	s_waitcnt lgkmcnt(0)
	v_add_f32_e32 v80, v90, v91
	ds_bpermute_b32 v81, v198, v80
	v_lshl_add_u64 v[86:87], v[92:93], 0, s[14:15]
	global_store_dwordx4 v[86:87], v[82:85], off sc1 nt
	s_nop 1
	s_and_saveexec_b64 s[0:1], s[6:7]
	s_cbranch_execz .LBB0_893
	s_waitcnt lgkmcnt(0)
	v_add_f32_e32 v82, v80, v81
	s_lshl_b32 s26, s51, 2
	v_lshlrev_b64 v[80:81], 6, v[186:187]
	s_ashr_i32 s27, s26, 31
	v_lshl_add_u64 v[80:81], s[18:19], 0, v[80:81]
	v_lshl_add_u64 v[80:81], s[26:27], 2, v[80:81]
	s_lshl_b32 s10, s45, 2
	v_lshl_add_u64 v[80:81], v[80:81], 0, s[10:11]
	global_store_dword v[80:81], v82, off
.LBB0_893:
	s_or_b64 exec, exec, s[0:1]
	v_add_u32_e32 v128, 0x90, v182
	v_ashrrev_i32_e32 v129, 31, v128
	s_waitcnt lgkmcnt(0)
	v_lshlrev_b64 v[80:81], 12, v[128:129]
	v_lshl_add_u64 v[84:85], v[184:185], 0, v[80:81]
	global_load_dwordx4 v[88:91], v[84:85], off offset:16
	global_load_dwordx4 v[92:95], v[84:85], off
	global_load_dwordx4 v[80:83], v[84:85], off offset:528
	s_nop 0
	global_load_dwordx4 v[84:87], v[84:85], off offset:512
	s_waitcnt vmcnt(14)
	v_pk_add_f32 v[78:79], v[78:79], v[126:127]
	v_pk_add_f32 v[76:77], v[76:77], v[124:125]
	v_pk_add_f32 v[122:123], v[74:75], v[122:123]
	v_pk_add_f32 v[74:75], v[72:73], v[120:121]
	v_mul_f32_e32 v72, v77, v77
	v_mul_f32_e32 v73, v79, v79
	v_fmac_f32_e32 v72, v76, v76
	v_fmac_f32_e32 v73, v78, v78
	v_add_f32_e32 v72, v72, v73
	v_mul_f32_e32 v73, v75, v75
	v_mul_f32_e32 v120, v123, v123
	v_fmac_f32_e32 v73, v74, v74
	v_fmac_f32_e32 v120, v122, v122
	v_lshlrev_b64 v[130:131], 10, v[188:189]
	v_add_f32_e32 v73, v73, v120
	v_lshl_add_u64 v[130:131], v[130:131], 0, v[180:181]
	v_add_f32_e32 v120, v72, v73
	v_cvt_pk_bf16_f32 v72, v76, v77
	v_cvt_pk_bf16_f32 v73, v78, v79
	s_waitcnt vmcnt(14)
	v_pk_add_f32 v[70:71], v[70:71], v[118:119]
	v_pk_add_f32 v[68:69], v[68:69], v[116:117]
	v_cvt_pk_bf16_f32 v74, v74, v75
	v_cvt_pk_bf16_f32 v75, v122, v123
	v_lshl_add_u64 v[76:77], v[130:131], 1, s[12:13]
	global_store_dwordx4 v[76:77], v[72:75], off sc1 nt
	s_nop 1
	v_pk_add_f32 v[72:73], v[66:67], v[114:115]
	v_mul_f32_e32 v66, v69, v69
	v_mul_f32_e32 v67, v71, v71
	v_pk_add_f32 v[64:65], v[64:65], v[112:113]
	v_fmac_f32_e32 v66, v68, v68
	v_fmac_f32_e32 v67, v70, v70
	v_add_f32_e32 v66, v66, v67
	v_mul_f32_e32 v67, v65, v65
	v_mul_f32_e32 v74, v73, v73
	v_fmac_f32_e32 v67, v64, v64
	v_fmac_f32_e32 v74, v72, v72
	v_add_f32_e32 v67, v67, v74
	v_add_f32_e32 v66, v66, v67
	v_add_f32_e32 v74, v120, v66
	ds_bpermute_b32 v75, v197, v74
	v_cvt_pk_bf16_f32 v66, v68, v69
	v_cvt_pk_bf16_f32 v68, v64, v65
	v_cvt_pk_bf16_f32 v67, v70, v71
	v_cvt_pk_bf16_f32 v69, v72, v73
	s_waitcnt lgkmcnt(0)
	v_add_f32_e32 v64, v74, v75
	ds_bpermute_b32 v65, v198, v64
	v_lshl_add_u64 v[70:71], v[76:77], 0, s[14:15]
	global_store_dwordx4 v[70:71], v[66:69], off sc1 nt
	s_nop 1
	s_and_saveexec_b64 s[0:1], s[6:7]
	s_cbranch_execz .LBB0_895
	s_waitcnt lgkmcnt(0)
	v_add_f32_e32 v66, v64, v65
	s_lshl_b32 s26, s51, 2
	v_lshlrev_b64 v[64:65], 6, v[188:189]
	s_ashr_i32 s27, s26, 31
	v_lshl_add_u64 v[64:65], s[18:19], 0, v[64:65]
	v_lshl_add_u64 v[64:65], s[26:27], 2, v[64:65]
	s_lshl_b32 s10, s45, 2
	v_lshl_add_u64 v[64:65], v[64:65], 0, s[10:11]
	global_store_dword v[64:65], v66, off
.LBB0_895:
	s_or_b64 exec, exec, s[0:1]
	v_add_u32_e32 v112, 0xa0, v182
	v_ashrrev_i32_e32 v113, 31, v112
	s_waitcnt lgkmcnt(0)
	v_lshlrev_b64 v[64:65], 12, v[112:113]
	v_lshl_add_u64 v[68:69], v[184:185], 0, v[64:65]
	global_load_dwordx4 v[72:75], v[68:69], off offset:16
	global_load_dwordx4 v[76:79], v[68:69], off
	global_load_dwordx4 v[64:67], v[68:69], off offset:528
	s_nop 0
	global_load_dwordx4 v[68:71], v[68:69], off offset:512
	s_waitcnt vmcnt(14)
	v_pk_add_f32 v[62:63], v[62:63], v[110:111]
	v_pk_add_f32 v[60:61], v[60:61], v[108:109]
	v_pk_add_f32 v[106:107], v[58:59], v[106:107]
	v_pk_add_f32 v[58:59], v[56:57], v[104:105]
	v_mul_f32_e32 v56, v61, v61
	v_mul_f32_e32 v57, v63, v63
	v_fmac_f32_e32 v56, v60, v60
	v_fmac_f32_e32 v57, v62, v62
	v_add_f32_e32 v56, v56, v57
	v_mul_f32_e32 v57, v59, v59
	v_mul_f32_e32 v104, v107, v107
	v_fmac_f32_e32 v57, v58, v58
	v_fmac_f32_e32 v104, v106, v106
	v_lshlrev_b64 v[114:115], 10, v[144:145]
	v_add_f32_e32 v57, v57, v104
	v_lshl_add_u64 v[114:115], v[114:115], 0, v[180:181]
	v_add_f32_e32 v104, v56, v57
	v_cvt_pk_bf16_f32 v56, v60, v61
	v_cvt_pk_bf16_f32 v57, v62, v63
	s_waitcnt vmcnt(14)
	v_pk_add_f32 v[54:55], v[54:55], v[102:103]
	v_pk_add_f32 v[52:53], v[52:53], v[100:101]
	v_cvt_pk_bf16_f32 v58, v58, v59
	v_cvt_pk_bf16_f32 v59, v106, v107
	v_lshl_add_u64 v[60:61], v[114:115], 1, s[12:13]
	global_store_dwordx4 v[60:61], v[56:59], off sc1 nt
	s_nop 1
	v_pk_add_f32 v[56:57], v[50:51], v[98:99]
	v_mul_f32_e32 v50, v53, v53
	v_mul_f32_e32 v51, v55, v55
	v_pk_add_f32 v[48:49], v[48:49], v[96:97]
	v_fmac_f32_e32 v50, v52, v52
	v_fmac_f32_e32 v51, v54, v54
	v_add_f32_e32 v50, v50, v51
	v_mul_f32_e32 v51, v49, v49
	v_mul_f32_e32 v58, v57, v57
	v_fmac_f32_e32 v51, v48, v48
	v_fmac_f32_e32 v58, v56, v56
	v_add_f32_e32 v51, v51, v58
	v_add_f32_e32 v50, v50, v51
	v_add_f32_e32 v58, v104, v50
	ds_bpermute_b32 v59, v197, v58
	v_cvt_pk_bf16_f32 v50, v52, v53
	v_cvt_pk_bf16_f32 v52, v48, v49
	v_cvt_pk_bf16_f32 v51, v54, v55
	v_cvt_pk_bf16_f32 v53, v56, v57
	s_waitcnt lgkmcnt(0)
	v_add_f32_e32 v48, v58, v59
	ds_bpermute_b32 v49, v198, v48
	v_lshl_add_u64 v[54:55], v[60:61], 0, s[14:15]
	global_store_dwordx4 v[54:55], v[50:53], off sc1 nt
	s_nop 1
	s_and_saveexec_b64 s[0:1], s[6:7]
	s_cbranch_execz .LBB0_897
	s_waitcnt lgkmcnt(0)
	v_add_f32_e32 v50, v48, v49
	s_lshl_b32 s26, s51, 2
	v_lshlrev_b64 v[48:49], 6, v[144:145]
	s_ashr_i32 s27, s26, 31
	v_lshl_add_u64 v[48:49], s[18:19], 0, v[48:49]
	v_lshl_add_u64 v[48:49], s[26:27], 2, v[48:49]
	s_lshl_b32 s10, s45, 2
	v_lshl_add_u64 v[48:49], v[48:49], 0, s[10:11]
	global_store_dword v[48:49], v50, off
.LBB0_897:
	s_or_b64 exec, exec, s[0:1]
	v_add_u32_e32 v96, 0xb0, v182
	v_ashrrev_i32_e32 v97, 31, v96
	s_waitcnt lgkmcnt(0)
	v_lshlrev_b64 v[48:49], 12, v[96:97]
	v_lshl_add_u64 v[52:53], v[184:185], 0, v[48:49]
	global_load_dwordx4 v[56:59], v[52:53], off offset:16
	global_load_dwordx4 v[60:63], v[52:53], off
	global_load_dwordx4 v[48:51], v[52:53], off offset:528
	s_nop 0
	global_load_dwordx4 v[52:55], v[52:53], off offset:512
	s_waitcnt vmcnt(14)
	v_pk_add_f32 v[46:47], v[46:47], v[94:95]
	v_pk_add_f32 v[44:45], v[44:45], v[92:93]
	v_pk_add_f32 v[90:91], v[42:43], v[90:91]
	v_pk_add_f32 v[42:43], v[40:41], v[88:89]
	v_mul_f32_e32 v40, v45, v45
	v_mul_f32_e32 v41, v47, v47
	v_fmac_f32_e32 v40, v44, v44
	v_fmac_f32_e32 v41, v46, v46
	v_add_f32_e32 v40, v40, v41
	v_mul_f32_e32 v41, v43, v43
	v_mul_f32_e32 v88, v91, v91
	v_fmac_f32_e32 v41, v42, v42
	v_fmac_f32_e32 v88, v90, v90
	v_lshlrev_b64 v[98:99], 10, v[128:129]
	v_add_f32_e32 v41, v41, v88
	v_lshl_add_u64 v[98:99], v[98:99], 0, v[180:181]
	v_add_f32_e32 v88, v40, v41
	v_cvt_pk_bf16_f32 v40, v44, v45
	v_cvt_pk_bf16_f32 v41, v46, v47
	s_waitcnt vmcnt(14)
	v_pk_add_f32 v[38:39], v[38:39], v[86:87]
	v_pk_add_f32 v[36:37], v[36:37], v[84:85]
	v_cvt_pk_bf16_f32 v42, v42, v43
	v_cvt_pk_bf16_f32 v43, v90, v91
	v_lshl_add_u64 v[44:45], v[98:99], 1, s[12:13]
	global_store_dwordx4 v[44:45], v[40:43], off sc1 nt
	s_nop 1
	v_pk_add_f32 v[40:41], v[34:35], v[82:83]
	v_mul_f32_e32 v34, v37, v37
	v_mul_f32_e32 v35, v39, v39
	v_pk_add_f32 v[32:33], v[32:33], v[80:81]
	v_fmac_f32_e32 v34, v36, v36
	v_fmac_f32_e32 v35, v38, v38
	v_add_f32_e32 v34, v34, v35
	v_mul_f32_e32 v35, v33, v33
	v_mul_f32_e32 v42, v41, v41
	v_fmac_f32_e32 v35, v32, v32
	v_fmac_f32_e32 v42, v40, v40
	v_add_f32_e32 v35, v35, v42
	v_add_f32_e32 v34, v34, v35
	v_add_f32_e32 v42, v88, v34
	ds_bpermute_b32 v43, v197, v42
	v_cvt_pk_bf16_f32 v34, v36, v37
	v_cvt_pk_bf16_f32 v36, v32, v33
	v_cvt_pk_bf16_f32 v35, v38, v39
	v_cvt_pk_bf16_f32 v37, v40, v41
	s_waitcnt lgkmcnt(0)
	v_add_f32_e32 v32, v42, v43
	ds_bpermute_b32 v33, v198, v32
	v_lshl_add_u64 v[38:39], v[44:45], 0, s[14:15]
	global_store_dwordx4 v[38:39], v[34:37], off sc1 nt
	s_nop 1
	s_and_saveexec_b64 s[0:1], s[6:7]
	s_cbranch_execz .LBB0_899
	s_waitcnt lgkmcnt(0)
	v_add_f32_e32 v34, v32, v33
	s_lshl_b32 s26, s51, 2
	v_lshlrev_b64 v[32:33], 6, v[128:129]
	s_ashr_i32 s27, s26, 31
	v_lshl_add_u64 v[32:33], s[18:19], 0, v[32:33]
	v_lshl_add_u64 v[32:33], s[26:27], 2, v[32:33]
	s_lshl_b32 s10, s45, 2
	v_lshl_add_u64 v[32:33], v[32:33], 0, s[10:11]
	global_store_dword v[32:33], v34, off
.LBB0_899:
	s_or_b64 exec, exec, s[0:1]
	s_waitcnt vmcnt(10)
	v_pk_add_f32 v[30:31], v[30:31], v[78:79]
	v_pk_add_f32 v[28:29], v[28:29], v[76:77]
	v_pk_add_f32 v[34:35], v[26:27], v[74:75]
	v_pk_add_f32 v[26:27], v[24:25], v[72:73]
	v_mul_f32_e32 v24, v29, v29
	v_mul_f32_e32 v25, v31, v31
	v_fmac_f32_e32 v24, v28, v28
	v_fmac_f32_e32 v25, v30, v30
	v_add_f32_e32 v24, v24, v25
	v_mul_f32_e32 v25, v27, v27
	v_mul_f32_e32 v36, v35, v35
	v_fmac_f32_e32 v25, v26, v26
	v_fmac_f32_e32 v36, v34, v34
	s_waitcnt lgkmcnt(0)
	v_lshlrev_b64 v[32:33], 10, v[112:113]
	v_add_f32_e32 v25, v25, v36
	v_lshl_add_u64 v[32:33], v[32:33], 0, v[180:181]
	v_add_f32_e32 v36, v24, v25
	v_cvt_pk_bf16_f32 v24, v28, v29
	v_cvt_pk_bf16_f32 v25, v30, v31
	s_waitcnt vmcnt(10)
	v_pk_add_f32 v[22:23], v[22:23], v[70:71]
	v_pk_add_f32 v[20:21], v[20:21], v[68:69]
	v_cvt_pk_bf16_f32 v26, v26, v27
	v_cvt_pk_bf16_f32 v27, v34, v35
	v_lshl_add_u64 v[28:29], v[32:33], 1, s[12:13]
	global_store_dwordx4 v[28:29], v[24:27], off sc1 nt
	s_nop 1
	v_pk_add_f32 v[24:25], v[18:19], v[66:67]
	v_mul_f32_e32 v18, v21, v21
	v_mul_f32_e32 v19, v23, v23
	v_pk_add_f32 v[16:17], v[16:17], v[64:65]
	v_fmac_f32_e32 v18, v20, v20
	v_fmac_f32_e32 v19, v22, v22
	v_add_f32_e32 v18, v18, v19
	v_mul_f32_e32 v19, v17, v17
	v_mul_f32_e32 v26, v25, v25
	v_fmac_f32_e32 v19, v16, v16
	v_fmac_f32_e32 v26, v24, v24
	v_add_f32_e32 v19, v19, v26
	v_add_f32_e32 v18, v18, v19
	v_add_f32_e32 v26, v36, v18
	ds_bpermute_b32 v27, v197, v26
	v_cvt_pk_bf16_f32 v18, v20, v21
	v_cvt_pk_bf16_f32 v20, v16, v17
	v_cvt_pk_bf16_f32 v19, v22, v23
	v_cvt_pk_bf16_f32 v21, v24, v25
	s_waitcnt lgkmcnt(0)
	v_add_f32_e32 v16, v26, v27
	ds_bpermute_b32 v17, v198, v16
	v_lshl_add_u64 v[22:23], v[28:29], 0, s[14:15]
	global_store_dwordx4 v[22:23], v[18:21], off sc1 nt
	s_nop 1
	s_and_saveexec_b64 s[0:1], s[6:7]
	s_cbranch_execz .LBB0_901
	s_waitcnt lgkmcnt(0)
	v_add_f32_e32 v18, v16, v17
	s_lshl_b32 s26, s51, 2
	v_lshlrev_b64 v[16:17], 6, v[112:113]
	s_ashr_i32 s27, s26, 31
	v_lshl_add_u64 v[16:17], s[18:19], 0, v[16:17]
	v_lshl_add_u64 v[16:17], s[26:27], 2, v[16:17]
	s_lshl_b32 s10, s45, 2
	v_lshl_add_u64 v[16:17], v[16:17], 0, s[10:11]
	global_store_dword v[16:17], v18, off
.LBB0_901:
	s_or_b64 exec, exec, s[0:1]
	s_waitcnt vmcnt(6)
	v_pk_add_f32 v[14:15], v[14:15], v[62:63]
	v_pk_add_f32 v[12:13], v[12:13], v[60:61]
	v_pk_add_f32 v[18:19], v[10:11], v[58:59]
	v_pk_add_f32 v[10:11], v[8:9], v[56:57]
	v_mul_f32_e32 v8, v13, v13
	v_mul_f32_e32 v9, v15, v15
	v_fmac_f32_e32 v8, v12, v12
	v_fmac_f32_e32 v9, v14, v14
	v_add_f32_e32 v8, v8, v9
	v_mul_f32_e32 v9, v11, v11
	v_mul_f32_e32 v20, v19, v19
	v_fmac_f32_e32 v9, v10, v10
	v_fmac_f32_e32 v20, v18, v18
	s_waitcnt lgkmcnt(0)
	v_lshlrev_b64 v[16:17], 10, v[96:97]
	v_add_f32_e32 v9, v9, v20
	v_lshl_add_u64 v[16:17], v[16:17], 0, v[180:181]
	v_add_f32_e32 v20, v8, v9
	v_cvt_pk_bf16_f32 v8, v12, v13
	v_cvt_pk_bf16_f32 v9, v14, v15
	s_waitcnt vmcnt(6)
	v_pk_add_f32 v[6:7], v[6:7], v[54:55]
	v_pk_add_f32 v[4:5], v[4:5], v[52:53]
	v_cvt_pk_bf16_f32 v10, v10, v11
	v_cvt_pk_bf16_f32 v11, v18, v19
	v_lshl_add_u64 v[12:13], v[16:17], 1, s[12:13]
	global_store_dwordx4 v[12:13], v[8:11], off sc1 nt
	s_nop 1
	v_pk_add_f32 v[8:9], v[2:3], v[50:51]
	v_mul_f32_e32 v2, v5, v5
	v_mul_f32_e32 v3, v7, v7
	v_pk_add_f32 v[0:1], v[0:1], v[48:49]
	v_fmac_f32_e32 v2, v4, v4
	v_fmac_f32_e32 v3, v6, v6
	v_add_f32_e32 v2, v2, v3
	v_mul_f32_e32 v3, v1, v1
	v_mul_f32_e32 v10, v9, v9
	v_fmac_f32_e32 v3, v0, v0
	v_fmac_f32_e32 v10, v8, v8
	v_add_f32_e32 v3, v3, v10
	v_add_f32_e32 v2, v2, v3
	v_add_f32_e32 v10, v20, v2
	ds_bpermute_b32 v11, v197, v10
	v_cvt_pk_bf16_f32 v2, v4, v5
	v_cvt_pk_bf16_f32 v4, v0, v1
	v_cvt_pk_bf16_f32 v3, v6, v7
	v_cvt_pk_bf16_f32 v5, v8, v9
	s_waitcnt lgkmcnt(0)
	v_add_f32_e32 v0, v10, v11
	ds_bpermute_b32 v1, v198, v0
	v_lshl_add_u64 v[6:7], v[12:13], 0, s[14:15]
	global_store_dwordx4 v[6:7], v[2:5], off sc1 nt
	s_nop 1
	s_and_saveexec_b64 s[0:1], s[6:7]
	s_cbranch_execz .LBB0_903
	s_waitcnt lgkmcnt(0)
	v_add_f32_e32 v2, v0, v1
	s_lshl_b32 s26, s51, 2
	v_lshlrev_b64 v[0:1], 6, v[96:97]
	s_ashr_i32 s27, s26, 31
	v_lshl_add_u64 v[0:1], s[18:19], 0, v[0:1]
	v_lshl_add_u64 v[0:1], s[26:27], 2, v[0:1]
	s_lshl_b32 s10, s45, 2
	v_lshl_add_u64 v[0:1], v[0:1], 0, s[10:11]
	global_store_dword v[0:1], v2, off

.LBB0_1097:
	v_lshl_add_u32 v202, s24, 8, v171
	v_lshl_or_b32 v128, s47, 8, v213
	v_ashrrev_i32_e32 v203, 31, v202
	v_lshlrev_b64 v[130:131], 11, v[202:203]
	v_ashrrev_i32_e32 v129, 31, v128
	v_lshl_add_u64 v[130:131], s[12:13], 0, v[130:131]
	v_lshlrev_b64 v[204:205], 1, v[128:129]
	v_lshl_add_u64 v[226:227], v[130:131], 0, v[204:205]
	global_load_dwordx4 v[218:221], v[226:227], off
	global_load_dwordx4 v[222:225], v[226:227], off offset:256
	v_or_b32_e32 v208, 16, v202
	v_or_b32_e32 v200, 32, v202
	v_or_b32_e32 v196, 48, v202
	v_add_u32_e32 v192, 0x80, v202
	v_add_u32_e32 v188, 0x90, v202
	v_ashrrev_i32_e32 v209, 31, v208
	v_ashrrev_i32_e32 v201, 31, v200
	v_ashrrev_i32_e32 v197, 31, v196
	v_ashrrev_i32_e32 v193, 31, v192
	v_ashrrev_i32_e32 v189, 31, v188
	v_lshlrev_b64 v[128:129], 11, v[208:209]
	v_lshlrev_b64 v[130:131], 11, v[200:201]
	v_lshlrev_b64 v[132:133], 11, v[196:197]
	v_lshlrev_b64 v[134:135], 11, v[192:193]
	v_lshlrev_b64 v[136:137], 11, v[188:189]
	v_lshl_add_u64 v[128:129], s[12:13], 0, v[128:129]
	v_lshl_add_u64 v[130:131], s[12:13], 0, v[130:131]
	v_lshl_add_u64 v[132:133], s[12:13], 0, v[132:133]
	v_lshl_add_u64 v[134:135], s[12:13], 0, v[134:135]
	v_lshl_add_u64 v[136:137], s[12:13], 0, v[136:137]
	v_lshl_add_u64 v[210:211], v[128:129], 0, v[204:205]
	v_lshl_add_u64 v[206:207], v[130:131], 0, v[204:205]
	v_lshl_add_u64 v[198:199], v[132:133], 0, v[204:205]
	v_lshl_add_u64 v[194:195], v[134:135], 0, v[204:205]
	v_lshl_add_u64 v[190:191], v[136:137], 0, v[204:205]
	global_load_dwordx4 v[164:167], v[210:211], off
	global_load_dwordx4 v[160:163], v[210:211], off offset:256
	global_load_dwordx4 v[156:159], v[206:207], off
	global_load_dwordx4 v[152:155], v[206:207], off offset:256
	global_load_dwordx4 v[148:151], v[198:199], off
	global_load_dwordx4 v[144:147], v[198:199], off offset:256
	global_load_dwordx4 v[140:143], v[194:195], off
	global_load_dwordx4 v[136:139], v[194:195], off offset:256
	global_load_dwordx4 v[132:135], v[190:191], off
	global_load_dwordx4 v[128:131], v[190:191], off offset:256
	v_lshl_add_u64 v[228:229], v[226:227], 0, s[14:15]
	s_waitcnt vmcnt(8)
	v_lshlrev_b32_e32 v230, 16, v218
	v_and_b32_e32 v231, 0xffff0000, v218
	v_lshlrev_b32_e32 v218, 16, v219
	v_and_b32_e32 v219, 0xffff0000, v219
	v_lshlrev_b32_e32 v232, 16, v220
	v_and_b32_e32 v233, 0xffff0000, v220
	v_lshlrev_b32_e32 v220, 16, v221
	v_and_b32_e32 v221, 0xffff0000, v221
	v_lshlrev_b32_e32 v234, 16, v222
	v_and_b32_e32 v235, 0xffff0000, v222
	v_lshlrev_b32_e32 v222, 16, v223
	v_and_b32_e32 v223, 0xffff0000, v223
	v_lshlrev_b32_e32 v236, 16, v224
	v_and_b32_e32 v237, 0xffff0000, v224
	v_lshlrev_b32_e32 v224, 16, v225
	v_and_b32_e32 v225, 0xffff0000, v225
	v_pk_add_f32 v[126:127], v[126:127], v[218:219]
	v_pk_add_f32 v[124:125], v[124:125], v[230:231]
	v_pk_add_f32 v[122:123], v[122:123], v[220:221]
	v_pk_add_f32 v[120:121], v[120:121], v[232:233]
	v_pk_add_f32 v[118:119], v[118:119], v[222:223]
	v_pk_add_f32 v[218:219], v[114:115], v[224:225]
	v_mul_f32_e32 v222, v125, v125
	v_mul_f32_e32 v223, v127, v127
	v_mul_f32_e32 v224, v121, v121
	v_mul_f32_e32 v225, v123, v123
	v_pk_add_f32 v[220:221], v[112:113], v[236:237]
	v_cvt_pk_bf16_f32 v112, v124, v125
	v_cvt_pk_bf16_f32 v113, v126, v127
	v_fmac_f32_e32 v222, v124, v124
	v_fmac_f32_e32 v223, v126, v126
	v_fmac_f32_e32 v224, v120, v120
	v_fmac_f32_e32 v225, v122, v122
	v_pk_add_f32 v[116:117], v[116:117], v[234:235]
	v_cvt_pk_bf16_f32 v114, v120, v121
	v_cvt_pk_bf16_f32 v115, v122, v123
	global_store_dwordx4 v[226:227], v[112:115], off sc1 nt
	s_nop 1
	v_add_f32_e32 v112, v222, v223
	v_add_f32_e32 v113, v224, v225
	v_mul_f32_e32 v121, v117, v117
	v_mul_f32_e32 v123, v119, v119
	v_add_f32_e32 v112, v112, v113
	v_mul_f32_e32 v113, v221, v221
	v_mul_f32_e32 v115, v219, v219
	v_fmac_f32_e32 v121, v116, v116
	v_fmac_f32_e32 v123, v118, v118
	v_fmac_f32_e32 v113, v220, v220
	v_fmac_f32_e32 v115, v218, v218
	v_add_f32_e32 v114, v121, v123
	v_add_f32_e32 v113, v113, v115
	v_add_f32_e32 v113, v114, v113
	v_and_b32_e32 v114, 64, v217
	v_add_f32_e32 v112, v112, v113
	v_xor_b32_e32 v113, 16, v217
	v_add_u32_e32 v121, 64, v114
	v_cmp_lt_i32_e32 vcc, v113, v121
	v_cvt_pk_bf16_f32 v114, v116, v117
	v_cvt_pk_bf16_f32 v115, v118, v119
	v_cndmask_b32_e32 v113, v217, v113, vcc
	v_lshlrev_b32_e32 v120, 2, v113
	ds_bpermute_b32 v113, v120, v112
	v_cvt_pk_bf16_f32 v116, v220, v221
	v_cvt_pk_bf16_f32 v117, v218, v219
	global_store_dwordx4 v[228:229], v[114:117], off sc1 nt
	s_nop 1
	s_waitcnt lgkmcnt(0)
	v_add_f32_e32 v112, v112, v113
	v_xor_b32_e32 v113, 32, v217
	v_cmp_lt_i32_e32 vcc, v113, v121
	s_nop 1
	v_cndmask_b32_e32 v113, v217, v113, vcc
	v_lshlrev_b32_e32 v121, 2, v113
	ds_bpermute_b32 v113, v121, v112
	s_and_saveexec_b64 s[0:1], s[6:7]
	s_cbranch_execz .LBB0_1099
	s_waitcnt lgkmcnt(0)
	v_add_f32_e32 v114, v112, v113
	s_lshl_b32 s24, s47, 2
	v_lshlrev_b64 v[112:113], 6, v[202:203]
	s_ashr_i32 s25, s24, 31
	v_lshl_add_u64 v[112:113], s[16:17], 0, v[112:113]
	v_lshl_add_u64 v[112:113], s[24:25], 2, v[112:113]
	s_lshl_b32 s4, s41, 2
	v_lshl_add_u64 v[112:113], v[112:113], 0, s[4:5]
	global_store_dword v[112:113], v114, off
.LBB0_1099:
	s_or_b64 exec, exec, s[0:1]
	v_lshlrev_b32_e32 v114, 16, v164
	v_and_b32_e32 v115, 0xffff0000, v164
	v_lshlrev_b32_e32 v116, 16, v165
	v_and_b32_e32 v117, 0xffff0000, v165
	v_lshlrev_b32_e32 v118, 16, v166
	v_and_b32_e32 v119, 0xffff0000, v166
	v_lshlrev_b32_e32 v122, 16, v167
	v_and_b32_e32 v123, 0xffff0000, v167
	v_pk_add_f32 v[110:111], v[110:111], v[116:117]
	v_pk_add_f32 v[108:109], v[108:109], v[114:115]
	v_pk_add_f32 v[114:115], v[106:107], v[122:123]
	v_pk_add_f32 v[106:107], v[104:105], v[118:119]
	v_mul_f32_e32 v104, v109, v109
	v_mul_f32_e32 v105, v111, v111
	v_fmac_f32_e32 v104, v108, v108
	v_fmac_f32_e32 v105, v110, v110
	v_add_f32_e32 v104, v104, v105
	v_mul_f32_e32 v105, v107, v107
	v_mul_f32_e32 v116, v115, v115
	v_fmac_f32_e32 v105, v106, v106
	v_fmac_f32_e32 v116, v114, v114
	v_lshlrev_b32_e32 v124, 16, v160
	v_and_b32_e32 v125, 0xffff0000, v160
	v_lshlrev_b32_e32 v126, 16, v161
	v_and_b32_e32 v127, 0xffff0000, v161
	v_add_f32_e32 v105, v105, v116
	v_lshlrev_b32_e32 v160, 16, v162
	v_and_b32_e32 v161, 0xffff0000, v162
	v_lshlrev_b32_e32 v162, 16, v163
	v_and_b32_e32 v163, 0xffff0000, v163
	v_add_f32_e32 v116, v104, v105
	v_cvt_pk_bf16_f32 v104, v108, v109
	v_cvt_pk_bf16_f32 v105, v110, v111
	v_pk_add_f32 v[102:103], v[102:103], v[126:127]
	v_pk_add_f32 v[100:101], v[100:101], v[124:125]
	v_cvt_pk_bf16_f32 v106, v106, v107
	v_cvt_pk_bf16_f32 v107, v114, v115
	global_store_dwordx4 v[210:211], v[104:107], off sc1 nt
	s_nop 1
	v_pk_add_f32 v[104:105], v[98:99], v[162:163]
	v_mul_f32_e32 v98, v101, v101
	v_mul_f32_e32 v99, v103, v103
	v_pk_add_f32 v[96:97], v[96:97], v[160:161]
	v_fmac_f32_e32 v98, v100, v100
	v_fmac_f32_e32 v99, v102, v102
	v_add_f32_e32 v98, v98, v99
	v_mul_f32_e32 v99, v97, v97
	v_mul_f32_e32 v106, v105, v105
	v_fmac_f32_e32 v99, v96, v96
	v_fmac_f32_e32 v106, v104, v104
	v_add_f32_e32 v99, v99, v106
	v_add_f32_e32 v98, v98, v99
	v_add_f32_e32 v106, v116, v98
	ds_bpermute_b32 v107, v120, v106
	v_cvt_pk_bf16_f32 v98, v100, v101
	v_cvt_pk_bf16_f32 v100, v96, v97
	s_waitcnt lgkmcnt(1)
	v_lshl_add_u64 v[112:113], v[210:211], 0, s[14:15]
	v_cvt_pk_bf16_f32 v99, v102, v103
	s_waitcnt lgkmcnt(0)
	v_add_f32_e32 v96, v106, v107
	ds_bpermute_b32 v97, v121, v96
	v_cvt_pk_bf16_f32 v101, v104, v105
	global_store_dwordx4 v[112:113], v[98:101], off sc1 nt
	s_nop 1
	s_and_saveexec_b64 s[0:1], s[6:7]
	s_cbranch_execz .LBB0_1101
	s_waitcnt lgkmcnt(0)
	v_add_f32_e32 v98, v96, v97
	s_lshl_b32 s24, s47, 2
	v_lshlrev_b64 v[96:97], 6, v[208:209]
	s_ashr_i32 s25, s24, 31
	v_lshl_add_u64 v[96:97], s[16:17], 0, v[96:97]
	v_lshl_add_u64 v[96:97], s[24:25], 2, v[96:97]
	s_lshl_b32 s4, s41, 2
	v_lshl_add_u64 v[96:97], v[96:97], 0, s[4:5]
	global_store_dword v[96:97], v98, off
.LBB0_1101:
	s_or_b64 exec, exec, s[0:1]
	v_add_u32_e32 v116, 0xa0, v202
	v_ashrrev_i32_e32 v117, 31, v116
	s_waitcnt lgkmcnt(0)
	v_lshlrev_b64 v[96:97], 11, v[116:117]
	v_add_u32_e32 v112, 0xb0, v202
	v_lshl_add_u64 v[96:97], s[12:13], 0, v[96:97]
	v_ashrrev_i32_e32 v113, 31, v112
	v_lshl_add_u64 v[118:119], v[96:97], 0, v[204:205]
	v_lshlrev_b64 v[96:97], 11, v[112:113]
	v_lshl_add_u64 v[96:97], s[12:13], 0, v[96:97]
	v_lshl_add_u64 v[114:115], v[96:97], 0, v[204:205]
	global_load_dwordx4 v[108:111], v[118:119], off
	global_load_dwordx4 v[104:107], v[118:119], off offset:256
	global_load_dwordx4 v[100:103], v[114:115], off
	global_load_dwordx4 v[96:99], v[114:115], off offset:256
	s_waitcnt vmcnt(14)
	v_lshlrev_b32_e32 v124, 16, v156
	v_and_b32_e32 v125, 0xffff0000, v156
	v_lshlrev_b32_e32 v126, 16, v157
	v_and_b32_e32 v127, 0xffff0000, v157
	v_lshlrev_b32_e32 v156, 16, v158
	v_and_b32_e32 v157, 0xffff0000, v158
	v_lshlrev_b32_e32 v158, 16, v159
	v_and_b32_e32 v159, 0xffff0000, v159
	v_pk_add_f32 v[94:95], v[94:95], v[126:127]
	v_pk_add_f32 v[92:93], v[92:93], v[124:125]
	v_pk_add_f32 v[124:125], v[90:91], v[158:159]
	v_pk_add_f32 v[90:91], v[88:89], v[156:157]
	v_mul_f32_e32 v88, v93, v93
	v_mul_f32_e32 v89, v95, v95
	v_fmac_f32_e32 v88, v92, v92
	v_fmac_f32_e32 v89, v94, v94
	v_add_f32_e32 v88, v88, v89
	v_mul_f32_e32 v89, v91, v91
	v_mul_f32_e32 v126, v125, v125
	v_fmac_f32_e32 v89, v90, v90
	v_fmac_f32_e32 v126, v124, v124
	v_lshlrev_b32_e32 v160, 16, v152
	v_and_b32_e32 v161, 0xffff0000, v152
	v_lshlrev_b32_e32 v152, 16, v153
	v_and_b32_e32 v153, 0xffff0000, v153
	v_add_f32_e32 v89, v89, v126
	v_lshlrev_b32_e32 v162, 16, v154
	v_and_b32_e32 v163, 0xffff0000, v154
	v_lshlrev_b32_e32 v154, 16, v155
	v_and_b32_e32 v155, 0xffff0000, v155
	v_add_f32_e32 v126, v88, v89
	v_cvt_pk_bf16_f32 v88, v92, v93
	v_cvt_pk_bf16_f32 v89, v94, v95
	v_pk_add_f32 v[86:87], v[86:87], v[152:153]
	v_pk_add_f32 v[84:85], v[84:85], v[160:161]
	v_cvt_pk_bf16_f32 v90, v90, v91
	v_cvt_pk_bf16_f32 v91, v124, v125
	global_store_dwordx4 v[206:207], v[88:91], off sc1 nt
	s_nop 1
	v_pk_add_f32 v[88:89], v[82:83], v[154:155]
	v_mul_f32_e32 v82, v85, v85
	v_mul_f32_e32 v83, v87, v87
	v_pk_add_f32 v[80:81], v[80:81], v[162:163]
	v_fmac_f32_e32 v82, v84, v84
	v_fmac_f32_e32 v83, v86, v86
	v_add_f32_e32 v82, v82, v83
	v_mul_f32_e32 v83, v81, v81
	v_mul_f32_e32 v90, v89, v89
	v_fmac_f32_e32 v83, v80, v80
	v_fmac_f32_e32 v90, v88, v88
	v_add_f32_e32 v83, v83, v90
	v_add_f32_e32 v82, v82, v83
	v_add_f32_e32 v90, v126, v82
	ds_bpermute_b32 v91, v120, v90
	v_cvt_pk_bf16_f32 v82, v84, v85
	v_cvt_pk_bf16_f32 v84, v80, v81
	v_lshl_add_u64 v[122:123], v[206:207], 0, s[14:15]
	v_cvt_pk_bf16_f32 v83, v86, v87
	s_waitcnt lgkmcnt(0)
	v_add_f32_e32 v80, v90, v91
	ds_bpermute_b32 v81, v121, v80
	v_cvt_pk_bf16_f32 v85, v88, v89
	global_store_dwordx4 v[122:123], v[82:85], off sc1 nt
	s_nop 1
	s_and_saveexec_b64 s[0:1], s[6:7]
	s_cbranch_execz .LBB0_1103
	s_waitcnt lgkmcnt(0)
	v_add_f32_e32 v82, v80, v81
	s_lshl_b32 s24, s47, 2
	v_lshlrev_b64 v[80:81], 6, v[200:201]
	s_ashr_i32 s25, s24, 31
	v_lshl_add_u64 v[80:81], s[16:17], 0, v[80:81]
	v_lshl_add_u64 v[80:81], s[24:25], 2, v[80:81]
	s_lshl_b32 s4, s41, 2
	v_lshl_add_u64 v[80:81], v[80:81], 0, s[4:5]
	global_store_dword v[80:81], v82, off
.LBB0_1103:
	s_or_b64 exec, exec, s[0:1]
	v_lshlrev_b32_e32 v82, 16, v148
	v_and_b32_e32 v83, 0xffff0000, v148
	v_lshlrev_b32_e32 v84, 16, v149
	v_and_b32_e32 v85, 0xffff0000, v149
	v_lshlrev_b32_e32 v86, 16, v150
	v_and_b32_e32 v87, 0xffff0000, v150
	v_lshlrev_b32_e32 v88, 16, v151
	v_and_b32_e32 v89, 0xffff0000, v151
	v_pk_add_f32 v[78:79], v[78:79], v[84:85]
	v_pk_add_f32 v[76:77], v[76:77], v[82:83]
	v_pk_add_f32 v[82:83], v[74:75], v[88:89]
	v_pk_add_f32 v[74:75], v[72:73], v[86:87]
	v_mul_f32_e32 v72, v77, v77
	v_mul_f32_e32 v73, v79, v79
	v_fmac_f32_e32 v72, v76, v76
	v_fmac_f32_e32 v73, v78, v78
	v_add_f32_e32 v72, v72, v73
	v_mul_f32_e32 v73, v75, v75
	v_mul_f32_e32 v84, v83, v83
	v_fmac_f32_e32 v73, v74, v74
	v_fmac_f32_e32 v84, v82, v82
	v_lshlrev_b32_e32 v90, 16, v144
	v_and_b32_e32 v91, 0xffff0000, v144
	v_lshlrev_b32_e32 v92, 16, v145
	v_and_b32_e32 v93, 0xffff0000, v145
	v_add_f32_e32 v73, v73, v84
	v_lshlrev_b32_e32 v122, 16, v147
	v_and_b32_e32 v123, 0xffff0000, v147
	v_add_f32_e32 v84, v72, v73
	v_cvt_pk_bf16_f32 v72, v76, v77
	v_cvt_pk_bf16_f32 v73, v78, v79
	v_pk_add_f32 v[70:71], v[70:71], v[92:93]
	v_pk_add_f32 v[68:69], v[68:69], v[90:91]
	v_lshlrev_b32_e32 v94, 16, v146
	v_and_b32_e32 v95, 0xffff0000, v146
	v_cvt_pk_bf16_f32 v74, v74, v75
	v_cvt_pk_bf16_f32 v75, v82, v83
	global_store_dwordx4 v[198:199], v[72:75], off sc1 nt
	s_nop 1
	v_pk_add_f32 v[72:73], v[66:67], v[122:123]
	v_mul_f32_e32 v66, v69, v69
	v_mul_f32_e32 v67, v71, v71
	v_pk_add_f32 v[64:65], v[64:65], v[94:95]
	v_fmac_f32_e32 v66, v68, v68
	v_fmac_f32_e32 v67, v70, v70
	v_add_f32_e32 v66, v66, v67
	v_mul_f32_e32 v67, v65, v65
	v_mul_f32_e32 v74, v73, v73
	v_fmac_f32_e32 v67, v64, v64
	v_fmac_f32_e32 v74, v72, v72
	v_add_f32_e32 v67, v67, v74
	v_add_f32_e32 v66, v66, v67
	v_add_f32_e32 v74, v84, v66
	ds_bpermute_b32 v75, v120, v74
	v_cvt_pk_bf16_f32 v66, v68, v69
	v_cvt_pk_bf16_f32 v68, v64, v65
	s_waitcnt lgkmcnt(1)
	v_lshl_add_u64 v[80:81], v[198:199], 0, s[14:15]
	v_cvt_pk_bf16_f32 v67, v70, v71
	s_waitcnt lgkmcnt(0)
	v_add_f32_e32 v64, v74, v75
	ds_bpermute_b32 v65, v121, v64
	v_cvt_pk_bf16_f32 v69, v72, v73
	global_store_dwordx4 v[80:81], v[66:69], off sc1 nt
	s_nop 1
	s_and_saveexec_b64 s[0:1], s[6:7]
	s_cbranch_execz .LBB0_1105
	s_waitcnt lgkmcnt(0)
	v_add_f32_e32 v66, v64, v65
	s_lshl_b32 s24, s47, 2
	v_lshlrev_b64 v[64:65], 6, v[196:197]
	s_ashr_i32 s25, s24, 31
	v_lshl_add_u64 v[64:65], s[16:17], 0, v[64:65]
	v_lshl_add_u64 v[64:65], s[24:25], 2, v[64:65]
	s_lshl_b32 s4, s41, 2
	v_lshl_add_u64 v[64:65], v[64:65], 0, s[4:5]
	global_store_dword v[64:65], v66, off
.LBB0_1105:
	s_or_b64 exec, exec, s[0:1]
	s_waitcnt vmcnt(16)
	v_lshlrev_b32_e32 v66, 16, v140
	v_and_b32_e32 v67, 0xffff0000, v140
	v_lshlrev_b32_e32 v68, 16, v141
	v_and_b32_e32 v69, 0xffff0000, v141
	v_lshlrev_b32_e32 v70, 16, v142
	v_and_b32_e32 v71, 0xffff0000, v142
	v_lshlrev_b32_e32 v72, 16, v143
	v_and_b32_e32 v73, 0xffff0000, v143
	v_pk_add_f32 v[62:63], v[62:63], v[68:69]
	v_pk_add_f32 v[60:61], v[60:61], v[66:67]
	v_pk_add_f32 v[66:67], v[58:59], v[72:73]
	v_pk_add_f32 v[58:59], v[56:57], v[70:71]
	v_mul_f32_e32 v56, v61, v61
	v_mul_f32_e32 v57, v63, v63
	v_fmac_f32_e32 v56, v60, v60
	v_fmac_f32_e32 v57, v62, v62
	v_add_f32_e32 v56, v56, v57
	v_mul_f32_e32 v57, v59, v59
	v_mul_f32_e32 v68, v67, v67
	v_fmac_f32_e32 v57, v58, v58
	v_fmac_f32_e32 v68, v66, v66
	v_lshlrev_b32_e32 v74, 16, v136
	v_and_b32_e32 v75, 0xffff0000, v136
	v_lshlrev_b32_e32 v76, 16, v137
	v_and_b32_e32 v77, 0xffff0000, v137
	v_add_f32_e32 v57, v57, v68
	v_lshlrev_b32_e32 v80, 16, v139
	v_and_b32_e32 v81, 0xffff0000, v139
	v_add_f32_e32 v68, v56, v57
	v_cvt_pk_bf16_f32 v56, v60, v61
	v_cvt_pk_bf16_f32 v57, v62, v63
	v_pk_add_f32 v[54:55], v[54:55], v[76:77]
	v_pk_add_f32 v[52:53], v[52:53], v[74:75]
	v_lshlrev_b32_e32 v78, 16, v138
	v_and_b32_e32 v79, 0xffff0000, v138
	v_cvt_pk_bf16_f32 v58, v58, v59
	v_cvt_pk_bf16_f32 v59, v66, v67
	global_store_dwordx4 v[194:195], v[56:59], off sc1 nt
	s_nop 1
	v_pk_add_f32 v[56:57], v[50:51], v[80:81]
	v_mul_f32_e32 v50, v53, v53
	v_mul_f32_e32 v51, v55, v55
	v_pk_add_f32 v[48:49], v[48:49], v[78:79]
	v_fmac_f32_e32 v50, v52, v52
	v_fmac_f32_e32 v51, v54, v54
	v_add_f32_e32 v50, v50, v51
	v_mul_f32_e32 v51, v49, v49
	v_mul_f32_e32 v58, v57, v57
	v_fmac_f32_e32 v51, v48, v48
	v_fmac_f32_e32 v58, v56, v56
	v_add_f32_e32 v51, v51, v58
	v_add_f32_e32 v50, v50, v51
	v_add_f32_e32 v58, v68, v50
	ds_bpermute_b32 v59, v120, v58
	v_cvt_pk_bf16_f32 v50, v52, v53
	v_cvt_pk_bf16_f32 v52, v48, v49
	s_waitcnt lgkmcnt(1)
	v_lshl_add_u64 v[64:65], v[194:195], 0, s[14:15]
	v_cvt_pk_bf16_f32 v51, v54, v55
	s_waitcnt lgkmcnt(0)
	v_add_f32_e32 v48, v58, v59
	ds_bpermute_b32 v49, v121, v48
	v_cvt_pk_bf16_f32 v53, v56, v57
	global_store_dwordx4 v[64:65], v[50:53], off sc1 nt
	s_nop 1
	s_and_saveexec_b64 s[0:1], s[6:7]
	s_cbranch_execz .LBB0_1107
	s_waitcnt lgkmcnt(0)
	v_add_f32_e32 v50, v48, v49
	s_lshl_b32 s24, s47, 2
	v_lshlrev_b64 v[48:49], 6, v[192:193]
	s_ashr_i32 s25, s24, 31
	v_lshl_add_u64 v[48:49], s[16:17], 0, v[48:49]
	v_lshl_add_u64 v[48:49], s[24:25], 2, v[48:49]
	s_lshl_b32 s4, s41, 2
	v_lshl_add_u64 v[48:49], v[48:49], 0, s[4:5]
	global_store_dword v[48:49], v50, off
.LBB0_1107:
	s_or_b64 exec, exec, s[0:1]
	v_lshlrev_b32_e32 v50, 16, v132
	v_and_b32_e32 v51, 0xffff0000, v132
	v_lshlrev_b32_e32 v52, 16, v133
	v_and_b32_e32 v53, 0xffff0000, v133
	v_lshlrev_b32_e32 v54, 16, v134
	v_and_b32_e32 v55, 0xffff0000, v134
	v_lshlrev_b32_e32 v56, 16, v135
	v_and_b32_e32 v57, 0xffff0000, v135
	v_pk_add_f32 v[46:47], v[46:47], v[52:53]
	v_pk_add_f32 v[44:45], v[44:45], v[50:51]
	v_pk_add_f32 v[50:51], v[42:43], v[56:57]
	v_pk_add_f32 v[42:43], v[40:41], v[54:55]
	v_mul_f32_e32 v40, v45, v45
	v_mul_f32_e32 v41, v47, v47
	v_fmac_f32_e32 v40, v44, v44
	v_fmac_f32_e32 v41, v46, v46
	v_add_f32_e32 v40, v40, v41
	v_mul_f32_e32 v41, v43, v43
	v_mul_f32_e32 v52, v51, v51
	v_fmac_f32_e32 v41, v42, v42
	v_fmac_f32_e32 v52, v50, v50
	v_lshlrev_b32_e32 v58, 16, v128
	v_and_b32_e32 v59, 0xffff0000, v128
	v_lshlrev_b32_e32 v60, 16, v129
	v_and_b32_e32 v61, 0xffff0000, v129
	v_add_f32_e32 v41, v41, v52
	v_lshlrev_b32_e32 v64, 16, v131
	v_and_b32_e32 v65, 0xffff0000, v131
	v_add_f32_e32 v52, v40, v41
	v_cvt_pk_bf16_f32 v40, v44, v45
	v_cvt_pk_bf16_f32 v41, v46, v47
	v_pk_add_f32 v[38:39], v[38:39], v[60:61]
	v_pk_add_f32 v[36:37], v[36:37], v[58:59]
	v_lshlrev_b32_e32 v62, 16, v130
	v_and_b32_e32 v63, 0xffff0000, v130
	v_cvt_pk_bf16_f32 v42, v42, v43
	v_cvt_pk_bf16_f32 v43, v50, v51
	global_store_dwordx4 v[190:191], v[40:43], off sc1 nt
	s_nop 1
	v_pk_add_f32 v[40:41], v[34:35], v[64:65]
	v_mul_f32_e32 v34, v37, v37
	v_mul_f32_e32 v35, v39, v39
	v_pk_add_f32 v[32:33], v[32:33], v[62:63]
	v_fmac_f32_e32 v34, v36, v36
	v_fmac_f32_e32 v35, v38, v38
	v_add_f32_e32 v34, v34, v35
	v_mul_f32_e32 v35, v33, v33
	v_mul_f32_e32 v42, v41, v41
	v_fmac_f32_e32 v35, v32, v32
	v_fmac_f32_e32 v42, v40, v40
	v_add_f32_e32 v35, v35, v42
	v_add_f32_e32 v34, v34, v35
	v_add_f32_e32 v42, v52, v34
	ds_bpermute_b32 v43, v120, v42
	v_cvt_pk_bf16_f32 v34, v36, v37
	v_cvt_pk_bf16_f32 v36, v32, v33
	s_waitcnt lgkmcnt(1)
	v_lshl_add_u64 v[48:49], v[190:191], 0, s[14:15]
	v_cvt_pk_bf16_f32 v35, v38, v39
	s_waitcnt lgkmcnt(0)
	v_add_f32_e32 v32, v42, v43
	ds_bpermute_b32 v33, v121, v32
	v_cvt_pk_bf16_f32 v37, v40, v41
	global_store_dwordx4 v[48:49], v[34:37], off sc1 nt
	s_nop 1
	s_and_saveexec_b64 s[0:1], s[6:7]
	s_cbranch_execz .LBB0_1109
	s_waitcnt lgkmcnt(0)
	v_add_f32_e32 v34, v32, v33
	s_lshl_b32 s24, s47, 2
	v_lshlrev_b64 v[32:33], 6, v[188:189]
	s_ashr_i32 s25, s24, 31
	v_lshl_add_u64 v[32:33], s[16:17], 0, v[32:33]
	v_lshl_add_u64 v[32:33], s[24:25], 2, v[32:33]
	s_lshl_b32 s4, s41, 2
	v_lshl_add_u64 v[32:33], v[32:33], 0, s[4:5]
	global_store_dword v[32:33], v34, off
.LBB0_1109:
	s_or_b64 exec, exec, s[0:1]
	s_waitcnt vmcnt(14)
	v_lshlrev_b32_e32 v34, 16, v108
	v_and_b32_e32 v35, 0xffff0000, v108
	v_lshlrev_b32_e32 v36, 16, v109
	v_and_b32_e32 v37, 0xffff0000, v109
	v_lshlrev_b32_e32 v38, 16, v110
	v_and_b32_e32 v39, 0xffff0000, v110
	v_lshlrev_b32_e32 v40, 16, v111
	v_and_b32_e32 v41, 0xffff0000, v111
	v_pk_add_f32 v[30:31], v[30:31], v[36:37]
	v_pk_add_f32 v[28:29], v[28:29], v[34:35]
	v_pk_add_f32 v[34:35], v[26:27], v[40:41]
	v_pk_add_f32 v[26:27], v[24:25], v[38:39]
	v_mul_f32_e32 v24, v29, v29
	v_mul_f32_e32 v25, v31, v31
	v_fmac_f32_e32 v24, v28, v28
	v_fmac_f32_e32 v25, v30, v30
	v_add_f32_e32 v24, v24, v25
	v_mul_f32_e32 v25, v27, v27
	v_mul_f32_e32 v36, v35, v35
	v_fmac_f32_e32 v25, v26, v26
	v_fmac_f32_e32 v36, v34, v34
	s_waitcnt vmcnt(14)
	v_lshlrev_b32_e32 v42, 16, v104
	v_and_b32_e32 v43, 0xffff0000, v104
	v_lshlrev_b32_e32 v44, 16, v105
	v_and_b32_e32 v45, 0xffff0000, v105
	v_add_f32_e32 v25, v25, v36
	v_lshlrev_b32_e32 v48, 16, v107
	v_and_b32_e32 v49, 0xffff0000, v107
	v_add_f32_e32 v36, v24, v25
	v_cvt_pk_bf16_f32 v24, v28, v29
	v_cvt_pk_bf16_f32 v25, v30, v31
	v_pk_add_f32 v[22:23], v[22:23], v[44:45]
	v_pk_add_f32 v[20:21], v[20:21], v[42:43]
	v_lshlrev_b32_e32 v46, 16, v106
	v_and_b32_e32 v47, 0xffff0000, v106
	v_cvt_pk_bf16_f32 v26, v26, v27
	v_cvt_pk_bf16_f32 v27, v34, v35
	global_store_dwordx4 v[118:119], v[24:27], off sc1 nt
	s_nop 1
	v_pk_add_f32 v[24:25], v[18:19], v[48:49]
	v_mul_f32_e32 v18, v21, v21
	v_mul_f32_e32 v19, v23, v23
	v_pk_add_f32 v[16:17], v[16:17], v[46:47]
	v_fmac_f32_e32 v18, v20, v20
	v_fmac_f32_e32 v19, v22, v22
	v_add_f32_e32 v18, v18, v19
	v_mul_f32_e32 v19, v17, v17
	v_mul_f32_e32 v26, v25, v25
	v_fmac_f32_e32 v19, v16, v16
	v_fmac_f32_e32 v26, v24, v24
	v_add_f32_e32 v19, v19, v26
	v_add_f32_e32 v18, v18, v19
	v_add_f32_e32 v26, v36, v18
	ds_bpermute_b32 v27, v120, v26
	v_cvt_pk_bf16_f32 v18, v20, v21
	v_cvt_pk_bf16_f32 v20, v16, v17
	s_waitcnt lgkmcnt(1)
	v_lshl_add_u64 v[32:33], v[118:119], 0, s[14:15]
	v_cvt_pk_bf16_f32 v19, v22, v23
	s_waitcnt lgkmcnt(0)
	v_add_f32_e32 v16, v26, v27
	ds_bpermute_b32 v17, v121, v16
	v_cvt_pk_bf16_f32 v21, v24, v25
	global_store_dwordx4 v[32:33], v[18:21], off sc1 nt
	s_nop 1
	s_and_saveexec_b64 s[0:1], s[6:7]
	s_cbranch_execz .LBB0_1111
	s_waitcnt lgkmcnt(0)
	v_add_f32_e32 v18, v16, v17
	s_lshl_b32 s24, s47, 2
	v_lshlrev_b64 v[16:17], 6, v[116:117]
	s_ashr_i32 s25, s24, 31
	v_lshl_add_u64 v[16:17], s[16:17], 0, v[16:17]
	v_lshl_add_u64 v[16:17], s[24:25], 2, v[16:17]
	s_lshl_b32 s4, s41, 2
	v_lshl_add_u64 v[16:17], v[16:17], 0, s[4:5]
	global_store_dword v[16:17], v18, off
.LBB0_1111:
	s_or_b64 exec, exec, s[0:1]
	s_waitcnt vmcnt(15)
	v_lshlrev_b32_e32 v18, 16, v100
	v_and_b32_e32 v19, 0xffff0000, v100
	v_lshlrev_b32_e32 v20, 16, v101
	v_and_b32_e32 v21, 0xffff0000, v101
	v_lshlrev_b32_e32 v22, 16, v102
	v_and_b32_e32 v23, 0xffff0000, v102
	v_lshlrev_b32_e32 v24, 16, v103
	v_and_b32_e32 v25, 0xffff0000, v103
	v_pk_add_f32 v[14:15], v[14:15], v[20:21]
	v_pk_add_f32 v[12:13], v[12:13], v[18:19]
	v_pk_add_f32 v[18:19], v[10:11], v[24:25]
	v_pk_add_f32 v[10:11], v[8:9], v[22:23]
	v_mul_f32_e32 v8, v13, v13
	v_mul_f32_e32 v9, v15, v15
	v_fmac_f32_e32 v8, v12, v12
	v_fmac_f32_e32 v9, v14, v14
	v_add_f32_e32 v8, v8, v9
	v_mul_f32_e32 v9, v11, v11
	v_mul_f32_e32 v20, v19, v19
	v_fmac_f32_e32 v9, v10, v10
	v_fmac_f32_e32 v20, v18, v18
	s_waitcnt vmcnt(15)
	v_lshlrev_b32_e32 v26, 16, v96
	v_and_b32_e32 v27, 0xffff0000, v96
	v_lshlrev_b32_e32 v28, 16, v97
	v_and_b32_e32 v29, 0xffff0000, v97
	v_add_f32_e32 v9, v9, v20
	v_lshlrev_b32_e32 v32, 16, v99
	v_and_b32_e32 v33, 0xffff0000, v99
	v_add_f32_e32 v20, v8, v9
	v_cvt_pk_bf16_f32 v8, v12, v13
	v_cvt_pk_bf16_f32 v9, v14, v15
	v_pk_add_f32 v[6:7], v[6:7], v[28:29]
	v_pk_add_f32 v[4:5], v[4:5], v[26:27]
	v_lshlrev_b32_e32 v30, 16, v98
	v_and_b32_e32 v31, 0xffff0000, v98
	v_cvt_pk_bf16_f32 v10, v10, v11
	v_cvt_pk_bf16_f32 v11, v18, v19
	global_store_dwordx4 v[114:115], v[8:11], off sc1 nt
	s_nop 1
	v_pk_add_f32 v[8:9], v[2:3], v[32:33]
	v_mul_f32_e32 v2, v5, v5
	v_mul_f32_e32 v3, v7, v7
	v_pk_add_f32 v[0:1], v[0:1], v[30:31]
	v_fmac_f32_e32 v2, v4, v4
	v_fmac_f32_e32 v3, v6, v6
	v_add_f32_e32 v2, v2, v3
	v_mul_f32_e32 v3, v1, v1
	v_mul_f32_e32 v10, v9, v9
	v_fmac_f32_e32 v3, v0, v0
	v_fmac_f32_e32 v10, v8, v8
	v_add_f32_e32 v3, v3, v10
	v_add_f32_e32 v2, v2, v3
	v_add_f32_e32 v10, v20, v2
	ds_bpermute_b32 v11, v120, v10
	v_cvt_pk_bf16_f32 v2, v4, v5
	v_cvt_pk_bf16_f32 v4, v0, v1
	s_waitcnt lgkmcnt(1)
	v_lshl_add_u64 v[16:17], v[114:115], 0, s[14:15]
	v_cvt_pk_bf16_f32 v3, v6, v7
	s_waitcnt lgkmcnt(0)
	v_add_f32_e32 v0, v10, v11
	ds_bpermute_b32 v1, v121, v0
	v_cvt_pk_bf16_f32 v5, v8, v9
	global_store_dwordx4 v[16:17], v[2:5], off sc1 nt
	s_nop 1
	s_and_saveexec_b64 s[0:1], s[6:7]
	s_cbranch_execz .LBB0_1113
	s_waitcnt lgkmcnt(0)
	v_add_f32_e32 v2, v0, v1
	s_lshl_b32 s24, s47, 2
	v_lshlrev_b64 v[0:1], 6, v[112:113]
	s_ashr_i32 s25, s24, 31
	v_lshl_add_u64 v[0:1], s[16:17], 0, v[0:1]
	v_lshl_add_u64 v[0:1], s[24:25], 2, v[0:1]
	s_lshl_b32 s4, s41, 2
	v_lshl_add_u64 v[0:1], v[0:1], 0, s[4:5]
	global_store_dword v[0:1], v2, off

.LBB0_2667:
	v_lshl_add_u32 v202, s24, 8, v171
	v_lshl_or_b32 v128, s45, 8, v213
	v_ashrrev_i32_e32 v203, 31, v202
	v_lshlrev_b64 v[130:131], 11, v[202:203]
	v_ashrrev_i32_e32 v129, 31, v128
	v_lshl_add_u64 v[130:131], s[12:13], 0, v[130:131]
	v_lshlrev_b64 v[204:205], 1, v[128:129]
	v_lshl_add_u64 v[226:227], v[130:131], 0, v[204:205]
	global_load_dwordx4 v[218:221], v[226:227], off
	global_load_dwordx4 v[222:225], v[226:227], off offset:256
	v_or_b32_e32 v208, 16, v202
	v_or_b32_e32 v200, 32, v202
	v_or_b32_e32 v196, 48, v202
	v_add_u32_e32 v192, 0x80, v202
	v_add_u32_e32 v188, 0x90, v202
	v_ashrrev_i32_e32 v209, 31, v208
	v_ashrrev_i32_e32 v201, 31, v200
	v_ashrrev_i32_e32 v197, 31, v196
	v_ashrrev_i32_e32 v193, 31, v192
	v_ashrrev_i32_e32 v189, 31, v188
	v_lshlrev_b64 v[128:129], 11, v[208:209]
	v_lshlrev_b64 v[130:131], 11, v[200:201]
	v_lshlrev_b64 v[132:133], 11, v[196:197]
	v_lshlrev_b64 v[134:135], 11, v[192:193]
	v_lshlrev_b64 v[136:137], 11, v[188:189]
	v_lshl_add_u64 v[128:129], s[12:13], 0, v[128:129]
	v_lshl_add_u64 v[130:131], s[12:13], 0, v[130:131]
	v_lshl_add_u64 v[132:133], s[12:13], 0, v[132:133]
	v_lshl_add_u64 v[134:135], s[12:13], 0, v[134:135]
	v_lshl_add_u64 v[136:137], s[12:13], 0, v[136:137]
	v_lshl_add_u64 v[210:211], v[128:129], 0, v[204:205]
	v_lshl_add_u64 v[206:207], v[130:131], 0, v[204:205]
	v_lshl_add_u64 v[198:199], v[132:133], 0, v[204:205]
	v_lshl_add_u64 v[194:195], v[134:135], 0, v[204:205]
	v_lshl_add_u64 v[190:191], v[136:137], 0, v[204:205]
	global_load_dwordx4 v[164:167], v[210:211], off
	global_load_dwordx4 v[160:163], v[210:211], off offset:256
	global_load_dwordx4 v[156:159], v[206:207], off
	global_load_dwordx4 v[152:155], v[206:207], off offset:256
	global_load_dwordx4 v[148:151], v[198:199], off
	global_load_dwordx4 v[144:147], v[198:199], off offset:256
	global_load_dwordx4 v[140:143], v[194:195], off
	global_load_dwordx4 v[136:139], v[194:195], off offset:256
	global_load_dwordx4 v[132:135], v[190:191], off
	global_load_dwordx4 v[128:131], v[190:191], off offset:256
	v_lshl_add_u64 v[228:229], v[226:227], 0, s[14:15]
	s_waitcnt vmcnt(8)
	v_lshlrev_b32_e32 v230, 16, v218
	v_and_b32_e32 v231, 0xffff0000, v218
	v_lshlrev_b32_e32 v218, 16, v219
	v_and_b32_e32 v219, 0xffff0000, v219
	v_lshlrev_b32_e32 v232, 16, v220
	v_and_b32_e32 v233, 0xffff0000, v220
	v_lshlrev_b32_e32 v220, 16, v221
	v_and_b32_e32 v221, 0xffff0000, v221
	v_lshlrev_b32_e32 v234, 16, v222
	v_and_b32_e32 v235, 0xffff0000, v222
	v_lshlrev_b32_e32 v222, 16, v223
	v_and_b32_e32 v223, 0xffff0000, v223
	v_lshlrev_b32_e32 v236, 16, v224
	v_and_b32_e32 v237, 0xffff0000, v224
	v_lshlrev_b32_e32 v224, 16, v225
	v_and_b32_e32 v225, 0xffff0000, v225
	v_pk_add_f32 v[126:127], v[126:127], v[218:219]
	v_pk_add_f32 v[124:125], v[124:125], v[230:231]
	v_pk_add_f32 v[122:123], v[122:123], v[220:221]
	v_pk_add_f32 v[120:121], v[120:121], v[232:233]
	v_pk_add_f32 v[118:119], v[118:119], v[222:223]
	v_pk_add_f32 v[218:219], v[114:115], v[224:225]
	v_mul_f32_e32 v222, v125, v125
	v_mul_f32_e32 v223, v127, v127
	v_mul_f32_e32 v224, v121, v121
	v_mul_f32_e32 v225, v123, v123
	v_pk_add_f32 v[220:221], v[112:113], v[236:237]
	v_cvt_pk_bf16_f32 v112, v124, v125
	v_cvt_pk_bf16_f32 v113, v126, v127
	v_fmac_f32_e32 v222, v124, v124
	v_fmac_f32_e32 v223, v126, v126
	v_fmac_f32_e32 v224, v120, v120
	v_fmac_f32_e32 v225, v122, v122
	v_pk_add_f32 v[116:117], v[116:117], v[234:235]
	v_cvt_pk_bf16_f32 v114, v120, v121
	v_cvt_pk_bf16_f32 v115, v122, v123
	global_store_dwordx4 v[226:227], v[112:115], off sc1 nt
	s_nop 1
	v_add_f32_e32 v112, v222, v223
	v_add_f32_e32 v113, v224, v225
	v_mul_f32_e32 v121, v117, v117
	v_mul_f32_e32 v123, v119, v119
	v_add_f32_e32 v112, v112, v113
	v_mul_f32_e32 v113, v221, v221
	v_mul_f32_e32 v115, v219, v219
	v_fmac_f32_e32 v121, v116, v116
	v_fmac_f32_e32 v123, v118, v118
	v_fmac_f32_e32 v113, v220, v220
	v_fmac_f32_e32 v115, v218, v218
	v_add_f32_e32 v114, v121, v123
	v_add_f32_e32 v113, v113, v115
	v_add_f32_e32 v113, v114, v113
	v_and_b32_e32 v114, 64, v217
	v_add_f32_e32 v112, v112, v113
	v_xor_b32_e32 v113, 16, v217
	v_add_u32_e32 v121, 64, v114
	v_cmp_lt_i32_e32 vcc, v113, v121
	v_cvt_pk_bf16_f32 v114, v116, v117
	v_cvt_pk_bf16_f32 v115, v118, v119
	v_cndmask_b32_e32 v113, v217, v113, vcc
	v_lshlrev_b32_e32 v120, 2, v113
	ds_bpermute_b32 v113, v120, v112
	v_cvt_pk_bf16_f32 v116, v220, v221
	v_cvt_pk_bf16_f32 v117, v218, v219
	global_store_dwordx4 v[228:229], v[114:117], off sc1 nt
	s_nop 1
	s_waitcnt lgkmcnt(0)
	v_add_f32_e32 v112, v112, v113
	v_xor_b32_e32 v113, 32, v217
	v_cmp_lt_i32_e32 vcc, v113, v121
	s_nop 1
	v_cndmask_b32_e32 v113, v217, v113, vcc
	v_lshlrev_b32_e32 v121, 2, v113
	ds_bpermute_b32 v113, v121, v112
	s_and_saveexec_b64 s[0:1], s[6:7]
	s_cbranch_execz .LBB0_2669
	s_waitcnt lgkmcnt(0)
	v_add_f32_e32 v114, v112, v113
	s_lshl_b32 s24, s45, 2
	v_lshlrev_b64 v[112:113], 6, v[202:203]
	s_ashr_i32 s25, s24, 31
	v_lshl_add_u64 v[112:113], s[16:17], 0, v[112:113]
	v_lshl_add_u64 v[112:113], s[24:25], 2, v[112:113]
	s_lshl_b32 s4, s40, 2
	v_lshl_add_u64 v[112:113], v[112:113], 0, s[4:5]
	global_store_dword v[112:113], v114, off
.LBB0_2669:
	s_or_b64 exec, exec, s[0:1]
	v_lshlrev_b32_e32 v114, 16, v164
	v_and_b32_e32 v115, 0xffff0000, v164
	v_lshlrev_b32_e32 v116, 16, v165
	v_and_b32_e32 v117, 0xffff0000, v165
	v_lshlrev_b32_e32 v118, 16, v166
	v_and_b32_e32 v119, 0xffff0000, v166
	v_lshlrev_b32_e32 v122, 16, v167
	v_and_b32_e32 v123, 0xffff0000, v167
	v_pk_add_f32 v[110:111], v[110:111], v[116:117]
	v_pk_add_f32 v[108:109], v[108:109], v[114:115]
	v_pk_add_f32 v[114:115], v[106:107], v[122:123]
	v_pk_add_f32 v[106:107], v[104:105], v[118:119]
	v_mul_f32_e32 v104, v109, v109
	v_mul_f32_e32 v105, v111, v111
	v_fmac_f32_e32 v104, v108, v108
	v_fmac_f32_e32 v105, v110, v110
	v_add_f32_e32 v104, v104, v105
	v_mul_f32_e32 v105, v107, v107
	v_mul_f32_e32 v116, v115, v115
	v_fmac_f32_e32 v105, v106, v106
	v_fmac_f32_e32 v116, v114, v114
	v_lshlrev_b32_e32 v124, 16, v160
	v_and_b32_e32 v125, 0xffff0000, v160
	v_lshlrev_b32_e32 v126, 16, v161
	v_and_b32_e32 v127, 0xffff0000, v161
	v_add_f32_e32 v105, v105, v116
	v_lshlrev_b32_e32 v160, 16, v162
	v_and_b32_e32 v161, 0xffff0000, v162
	v_lshlrev_b32_e32 v162, 16, v163
	v_and_b32_e32 v163, 0xffff0000, v163
	v_add_f32_e32 v116, v104, v105
	v_cvt_pk_bf16_f32 v104, v108, v109
	v_cvt_pk_bf16_f32 v105, v110, v111
	v_pk_add_f32 v[102:103], v[102:103], v[126:127]
	v_pk_add_f32 v[100:101], v[100:101], v[124:125]
	v_cvt_pk_bf16_f32 v106, v106, v107
	v_cvt_pk_bf16_f32 v107, v114, v115
	global_store_dwordx4 v[210:211], v[104:107], off sc1 nt
	s_nop 1
	v_pk_add_f32 v[104:105], v[98:99], v[162:163]
	v_mul_f32_e32 v98, v101, v101
	v_mul_f32_e32 v99, v103, v103
	v_pk_add_f32 v[96:97], v[96:97], v[160:161]
	v_fmac_f32_e32 v98, v100, v100
	v_fmac_f32_e32 v99, v102, v102
	v_add_f32_e32 v98, v98, v99
	v_mul_f32_e32 v99, v97, v97
	v_mul_f32_e32 v106, v105, v105
	v_fmac_f32_e32 v99, v96, v96
	v_fmac_f32_e32 v106, v104, v104
	v_add_f32_e32 v99, v99, v106
	v_add_f32_e32 v98, v98, v99
	v_add_f32_e32 v106, v116, v98
	ds_bpermute_b32 v107, v120, v106
	v_cvt_pk_bf16_f32 v98, v100, v101
	v_cvt_pk_bf16_f32 v100, v96, v97
	s_waitcnt lgkmcnt(1)
	v_lshl_add_u64 v[112:113], v[210:211], 0, s[14:15]
	v_cvt_pk_bf16_f32 v99, v102, v103
	s_waitcnt lgkmcnt(0)
	v_add_f32_e32 v96, v106, v107
	ds_bpermute_b32 v97, v121, v96
	v_cvt_pk_bf16_f32 v101, v104, v105
	global_store_dwordx4 v[112:113], v[98:101], off sc1 nt
	s_nop 1
	s_and_saveexec_b64 s[0:1], s[6:7]
	s_cbranch_execz .LBB0_2671
	s_waitcnt lgkmcnt(0)
	v_add_f32_e32 v98, v96, v97
	s_lshl_b32 s24, s45, 2
	v_lshlrev_b64 v[96:97], 6, v[208:209]
	s_ashr_i32 s25, s24, 31
	v_lshl_add_u64 v[96:97], s[16:17], 0, v[96:97]
	v_lshl_add_u64 v[96:97], s[24:25], 2, v[96:97]
	s_lshl_b32 s4, s40, 2
	v_lshl_add_u64 v[96:97], v[96:97], 0, s[4:5]
	global_store_dword v[96:97], v98, off
.LBB0_2671:
	s_or_b64 exec, exec, s[0:1]
	v_add_u32_e32 v116, 0xa0, v202
	v_ashrrev_i32_e32 v117, 31, v116
	s_waitcnt lgkmcnt(0)
	v_lshlrev_b64 v[96:97], 11, v[116:117]
	v_add_u32_e32 v112, 0xb0, v202
	v_lshl_add_u64 v[96:97], s[12:13], 0, v[96:97]
	v_ashrrev_i32_e32 v113, 31, v112
	v_lshl_add_u64 v[118:119], v[96:97], 0, v[204:205]
	v_lshlrev_b64 v[96:97], 11, v[112:113]
	v_lshl_add_u64 v[96:97], s[12:13], 0, v[96:97]
	v_lshl_add_u64 v[114:115], v[96:97], 0, v[204:205]
	global_load_dwordx4 v[108:111], v[118:119], off
	global_load_dwordx4 v[104:107], v[118:119], off offset:256
	global_load_dwordx4 v[100:103], v[114:115], off
	global_load_dwordx4 v[96:99], v[114:115], off offset:256
	s_waitcnt vmcnt(14)
	v_lshlrev_b32_e32 v124, 16, v156
	v_and_b32_e32 v125, 0xffff0000, v156
	v_lshlrev_b32_e32 v126, 16, v157
	v_and_b32_e32 v127, 0xffff0000, v157
	v_lshlrev_b32_e32 v156, 16, v158
	v_and_b32_e32 v157, 0xffff0000, v158
	v_lshlrev_b32_e32 v158, 16, v159
	v_and_b32_e32 v159, 0xffff0000, v159
	v_pk_add_f32 v[94:95], v[94:95], v[126:127]
	v_pk_add_f32 v[92:93], v[92:93], v[124:125]
	v_pk_add_f32 v[124:125], v[90:91], v[158:159]
	v_pk_add_f32 v[90:91], v[88:89], v[156:157]
	v_mul_f32_e32 v88, v93, v93
	v_mul_f32_e32 v89, v95, v95
	v_fmac_f32_e32 v88, v92, v92
	v_fmac_f32_e32 v89, v94, v94
	v_add_f32_e32 v88, v88, v89
	v_mul_f32_e32 v89, v91, v91
	v_mul_f32_e32 v126, v125, v125
	v_fmac_f32_e32 v89, v90, v90
	v_fmac_f32_e32 v126, v124, v124
	v_lshlrev_b32_e32 v160, 16, v152
	v_and_b32_e32 v161, 0xffff0000, v152
	v_lshlrev_b32_e32 v152, 16, v153
	v_and_b32_e32 v153, 0xffff0000, v153
	v_add_f32_e32 v89, v89, v126
	v_lshlrev_b32_e32 v162, 16, v154
	v_and_b32_e32 v163, 0xffff0000, v154
	v_lshlrev_b32_e32 v154, 16, v155
	v_and_b32_e32 v155, 0xffff0000, v155
	v_add_f32_e32 v126, v88, v89
	v_cvt_pk_bf16_f32 v88, v92, v93
	v_cvt_pk_bf16_f32 v89, v94, v95
	v_pk_add_f32 v[86:87], v[86:87], v[152:153]
	v_pk_add_f32 v[84:85], v[84:85], v[160:161]
	v_cvt_pk_bf16_f32 v90, v90, v91
	v_cvt_pk_bf16_f32 v91, v124, v125
	global_store_dwordx4 v[206:207], v[88:91], off sc1 nt
	s_nop 1
	v_pk_add_f32 v[88:89], v[82:83], v[154:155]
	v_mul_f32_e32 v82, v85, v85
	v_mul_f32_e32 v83, v87, v87
	v_pk_add_f32 v[80:81], v[80:81], v[162:163]
	v_fmac_f32_e32 v82, v84, v84
	v_fmac_f32_e32 v83, v86, v86
	v_add_f32_e32 v82, v82, v83
	v_mul_f32_e32 v83, v81, v81
	v_mul_f32_e32 v90, v89, v89
	v_fmac_f32_e32 v83, v80, v80
	v_fmac_f32_e32 v90, v88, v88
	v_add_f32_e32 v83, v83, v90
	v_add_f32_e32 v82, v82, v83
	v_add_f32_e32 v90, v126, v82
	ds_bpermute_b32 v91, v120, v90
	v_cvt_pk_bf16_f32 v82, v84, v85
	v_cvt_pk_bf16_f32 v84, v80, v81
	v_lshl_add_u64 v[122:123], v[206:207], 0, s[14:15]
	v_cvt_pk_bf16_f32 v83, v86, v87
	s_waitcnt lgkmcnt(0)
	v_add_f32_e32 v80, v90, v91
	ds_bpermute_b32 v81, v121, v80
	v_cvt_pk_bf16_f32 v85, v88, v89
	global_store_dwordx4 v[122:123], v[82:85], off sc1 nt
	s_nop 1
	s_and_saveexec_b64 s[0:1], s[6:7]
	s_cbranch_execz .LBB0_2673
	s_waitcnt lgkmcnt(0)
	v_add_f32_e32 v82, v80, v81
	s_lshl_b32 s24, s45, 2
	v_lshlrev_b64 v[80:81], 6, v[200:201]
	s_ashr_i32 s25, s24, 31
	v_lshl_add_u64 v[80:81], s[16:17], 0, v[80:81]
	v_lshl_add_u64 v[80:81], s[24:25], 2, v[80:81]
	s_lshl_b32 s4, s40, 2
	v_lshl_add_u64 v[80:81], v[80:81], 0, s[4:5]
	global_store_dword v[80:81], v82, off
.LBB0_2673:
	s_or_b64 exec, exec, s[0:1]
	v_lshlrev_b32_e32 v82, 16, v148
	v_and_b32_e32 v83, 0xffff0000, v148
	v_lshlrev_b32_e32 v84, 16, v149
	v_and_b32_e32 v85, 0xffff0000, v149
	v_lshlrev_b32_e32 v86, 16, v150
	v_and_b32_e32 v87, 0xffff0000, v150
	v_lshlrev_b32_e32 v88, 16, v151
	v_and_b32_e32 v89, 0xffff0000, v151
	v_pk_add_f32 v[78:79], v[78:79], v[84:85]
	v_pk_add_f32 v[76:77], v[76:77], v[82:83]
	v_pk_add_f32 v[82:83], v[74:75], v[88:89]
	v_pk_add_f32 v[74:75], v[72:73], v[86:87]
	v_mul_f32_e32 v72, v77, v77
	v_mul_f32_e32 v73, v79, v79
	v_fmac_f32_e32 v72, v76, v76
	v_fmac_f32_e32 v73, v78, v78
	v_add_f32_e32 v72, v72, v73
	v_mul_f32_e32 v73, v75, v75
	v_mul_f32_e32 v84, v83, v83
	v_fmac_f32_e32 v73, v74, v74
	v_fmac_f32_e32 v84, v82, v82
	v_lshlrev_b32_e32 v90, 16, v144
	v_and_b32_e32 v91, 0xffff0000, v144
	v_lshlrev_b32_e32 v92, 16, v145
	v_and_b32_e32 v93, 0xffff0000, v145
	v_add_f32_e32 v73, v73, v84
	v_lshlrev_b32_e32 v122, 16, v147
	v_and_b32_e32 v123, 0xffff0000, v147
	v_add_f32_e32 v84, v72, v73
	v_cvt_pk_bf16_f32 v72, v76, v77
	v_cvt_pk_bf16_f32 v73, v78, v79
	v_pk_add_f32 v[70:71], v[70:71], v[92:93]
	v_pk_add_f32 v[68:69], v[68:69], v[90:91]
	v_lshlrev_b32_e32 v94, 16, v146
	v_and_b32_e32 v95, 0xffff0000, v146
	v_cvt_pk_bf16_f32 v74, v74, v75
	v_cvt_pk_bf16_f32 v75, v82, v83
	global_store_dwordx4 v[198:199], v[72:75], off sc1 nt
	s_nop 1
	v_pk_add_f32 v[72:73], v[66:67], v[122:123]
	v_mul_f32_e32 v66, v69, v69
	v_mul_f32_e32 v67, v71, v71
	v_pk_add_f32 v[64:65], v[64:65], v[94:95]
	v_fmac_f32_e32 v66, v68, v68
	v_fmac_f32_e32 v67, v70, v70
	v_add_f32_e32 v66, v66, v67
	v_mul_f32_e32 v67, v65, v65
	v_mul_f32_e32 v74, v73, v73
	v_fmac_f32_e32 v67, v64, v64
	v_fmac_f32_e32 v74, v72, v72
	v_add_f32_e32 v67, v67, v74
	v_add_f32_e32 v66, v66, v67
	v_add_f32_e32 v74, v84, v66
	ds_bpermute_b32 v75, v120, v74
	v_cvt_pk_bf16_f32 v66, v68, v69
	v_cvt_pk_bf16_f32 v68, v64, v65
	s_waitcnt lgkmcnt(1)
	v_lshl_add_u64 v[80:81], v[198:199], 0, s[14:15]
	v_cvt_pk_bf16_f32 v67, v70, v71
	s_waitcnt lgkmcnt(0)
	v_add_f32_e32 v64, v74, v75
	ds_bpermute_b32 v65, v121, v64
	v_cvt_pk_bf16_f32 v69, v72, v73
	global_store_dwordx4 v[80:81], v[66:69], off sc1 nt
	s_nop 1
	s_and_saveexec_b64 s[0:1], s[6:7]
	s_cbranch_execz .LBB0_2675
	s_waitcnt lgkmcnt(0)
	v_add_f32_e32 v66, v64, v65
	s_lshl_b32 s24, s45, 2
	v_lshlrev_b64 v[64:65], 6, v[196:197]
	s_ashr_i32 s25, s24, 31
	v_lshl_add_u64 v[64:65], s[16:17], 0, v[64:65]
	v_lshl_add_u64 v[64:65], s[24:25], 2, v[64:65]
	s_lshl_b32 s4, s40, 2
	v_lshl_add_u64 v[64:65], v[64:65], 0, s[4:5]
	global_store_dword v[64:65], v66, off
.LBB0_2675:
	s_or_b64 exec, exec, s[0:1]
	s_waitcnt vmcnt(16)
	v_lshlrev_b32_e32 v66, 16, v140
	v_and_b32_e32 v67, 0xffff0000, v140
	v_lshlrev_b32_e32 v68, 16, v141
	v_and_b32_e32 v69, 0xffff0000, v141
	v_lshlrev_b32_e32 v70, 16, v142
	v_and_b32_e32 v71, 0xffff0000, v142
	v_lshlrev_b32_e32 v72, 16, v143
	v_and_b32_e32 v73, 0xffff0000, v143
	v_pk_add_f32 v[62:63], v[62:63], v[68:69]
	v_pk_add_f32 v[60:61], v[60:61], v[66:67]
	v_pk_add_f32 v[66:67], v[58:59], v[72:73]
	v_pk_add_f32 v[58:59], v[56:57], v[70:71]
	v_mul_f32_e32 v56, v61, v61
	v_mul_f32_e32 v57, v63, v63
	v_fmac_f32_e32 v56, v60, v60
	v_fmac_f32_e32 v57, v62, v62
	v_add_f32_e32 v56, v56, v57
	v_mul_f32_e32 v57, v59, v59
	v_mul_f32_e32 v68, v67, v67
	v_fmac_f32_e32 v57, v58, v58
	v_fmac_f32_e32 v68, v66, v66
	v_lshlrev_b32_e32 v74, 16, v136
	v_and_b32_e32 v75, 0xffff0000, v136
	v_lshlrev_b32_e32 v76, 16, v137
	v_and_b32_e32 v77, 0xffff0000, v137
	v_add_f32_e32 v57, v57, v68
	v_lshlrev_b32_e32 v80, 16, v139
	v_and_b32_e32 v81, 0xffff0000, v139
	v_add_f32_e32 v68, v56, v57
	v_cvt_pk_bf16_f32 v56, v60, v61
	v_cvt_pk_bf16_f32 v57, v62, v63
	v_pk_add_f32 v[54:55], v[54:55], v[76:77]
	v_pk_add_f32 v[52:53], v[52:53], v[74:75]
	v_lshlrev_b32_e32 v78, 16, v138
	v_and_b32_e32 v79, 0xffff0000, v138
	v_cvt_pk_bf16_f32 v58, v58, v59
	v_cvt_pk_bf16_f32 v59, v66, v67
	global_store_dwordx4 v[194:195], v[56:59], off sc1 nt
	s_nop 1
	v_pk_add_f32 v[56:57], v[50:51], v[80:81]
	v_mul_f32_e32 v50, v53, v53
	v_mul_f32_e32 v51, v55, v55
	v_pk_add_f32 v[48:49], v[48:49], v[78:79]
	v_fmac_f32_e32 v50, v52, v52
	v_fmac_f32_e32 v51, v54, v54
	v_add_f32_e32 v50, v50, v51
	v_mul_f32_e32 v51, v49, v49
	v_mul_f32_e32 v58, v57, v57
	v_fmac_f32_e32 v51, v48, v48
	v_fmac_f32_e32 v58, v56, v56
	v_add_f32_e32 v51, v51, v58
	v_add_f32_e32 v50, v50, v51
	v_add_f32_e32 v58, v68, v50
	ds_bpermute_b32 v59, v120, v58
	v_cvt_pk_bf16_f32 v50, v52, v53
	v_cvt_pk_bf16_f32 v52, v48, v49
	s_waitcnt lgkmcnt(1)
	v_lshl_add_u64 v[64:65], v[194:195], 0, s[14:15]
	v_cvt_pk_bf16_f32 v51, v54, v55
	s_waitcnt lgkmcnt(0)
	v_add_f32_e32 v48, v58, v59
	ds_bpermute_b32 v49, v121, v48
	v_cvt_pk_bf16_f32 v53, v56, v57
	global_store_dwordx4 v[64:65], v[50:53], off sc1 nt
	s_nop 1
	s_and_saveexec_b64 s[0:1], s[6:7]
	s_cbranch_execz .LBB0_2677
	s_waitcnt lgkmcnt(0)
	v_add_f32_e32 v50, v48, v49
	s_lshl_b32 s24, s45, 2
	v_lshlrev_b64 v[48:49], 6, v[192:193]
	s_ashr_i32 s25, s24, 31
	v_lshl_add_u64 v[48:49], s[16:17], 0, v[48:49]
	v_lshl_add_u64 v[48:49], s[24:25], 2, v[48:49]
	s_lshl_b32 s4, s40, 2
	v_lshl_add_u64 v[48:49], v[48:49], 0, s[4:5]
	global_store_dword v[48:49], v50, off
.LBB0_2677:
	s_or_b64 exec, exec, s[0:1]
	v_lshlrev_b32_e32 v50, 16, v132
	v_and_b32_e32 v51, 0xffff0000, v132
	v_lshlrev_b32_e32 v52, 16, v133
	v_and_b32_e32 v53, 0xffff0000, v133
	v_lshlrev_b32_e32 v54, 16, v134
	v_and_b32_e32 v55, 0xffff0000, v134
	v_lshlrev_b32_e32 v56, 16, v135
	v_and_b32_e32 v57, 0xffff0000, v135
	v_pk_add_f32 v[46:47], v[46:47], v[52:53]
	v_pk_add_f32 v[44:45], v[44:45], v[50:51]
	v_pk_add_f32 v[50:51], v[42:43], v[56:57]
	v_pk_add_f32 v[42:43], v[40:41], v[54:55]
	v_mul_f32_e32 v40, v45, v45
	v_mul_f32_e32 v41, v47, v47
	v_fmac_f32_e32 v40, v44, v44
	v_fmac_f32_e32 v41, v46, v46
	v_add_f32_e32 v40, v40, v41
	v_mul_f32_e32 v41, v43, v43
	v_mul_f32_e32 v52, v51, v51
	v_fmac_f32_e32 v41, v42, v42
	v_fmac_f32_e32 v52, v50, v50
	v_lshlrev_b32_e32 v58, 16, v128
	v_and_b32_e32 v59, 0xffff0000, v128
	v_lshlrev_b32_e32 v60, 16, v129
	v_and_b32_e32 v61, 0xffff0000, v129
	v_add_f32_e32 v41, v41, v52
	v_lshlrev_b32_e32 v64, 16, v131
	v_and_b32_e32 v65, 0xffff0000, v131
	v_add_f32_e32 v52, v40, v41
	v_cvt_pk_bf16_f32 v40, v44, v45
	v_cvt_pk_bf16_f32 v41, v46, v47
	v_pk_add_f32 v[38:39], v[38:39], v[60:61]
	v_pk_add_f32 v[36:37], v[36:37], v[58:59]
	v_lshlrev_b32_e32 v62, 16, v130
	v_and_b32_e32 v63, 0xffff0000, v130
	v_cvt_pk_bf16_f32 v42, v42, v43
	v_cvt_pk_bf16_f32 v43, v50, v51
	global_store_dwordx4 v[190:191], v[40:43], off sc1 nt
	s_nop 1
	v_pk_add_f32 v[40:41], v[34:35], v[64:65]
	v_mul_f32_e32 v34, v37, v37
	v_mul_f32_e32 v35, v39, v39
	v_pk_add_f32 v[32:33], v[32:33], v[62:63]
	v_fmac_f32_e32 v34, v36, v36
	v_fmac_f32_e32 v35, v38, v38
	v_add_f32_e32 v34, v34, v35
	v_mul_f32_e32 v35, v33, v33
	v_mul_f32_e32 v42, v41, v41
	v_fmac_f32_e32 v35, v32, v32
	v_fmac_f32_e32 v42, v40, v40
	v_add_f32_e32 v35, v35, v42
	v_add_f32_e32 v34, v34, v35
	v_add_f32_e32 v42, v52, v34
	ds_bpermute_b32 v43, v120, v42
	v_cvt_pk_bf16_f32 v34, v36, v37
	v_cvt_pk_bf16_f32 v36, v32, v33
	s_waitcnt lgkmcnt(1)
	v_lshl_add_u64 v[48:49], v[190:191], 0, s[14:15]
	v_cvt_pk_bf16_f32 v35, v38, v39
	s_waitcnt lgkmcnt(0)
	v_add_f32_e32 v32, v42, v43
	ds_bpermute_b32 v33, v121, v32
	v_cvt_pk_bf16_f32 v37, v40, v41
	global_store_dwordx4 v[48:49], v[34:37], off sc1 nt
	s_nop 1
	s_and_saveexec_b64 s[0:1], s[6:7]
	s_cbranch_execz .LBB0_2679
	s_waitcnt lgkmcnt(0)
	v_add_f32_e32 v34, v32, v33
	s_lshl_b32 s24, s45, 2
	v_lshlrev_b64 v[32:33], 6, v[188:189]
	s_ashr_i32 s25, s24, 31
	v_lshl_add_u64 v[32:33], s[16:17], 0, v[32:33]
	v_lshl_add_u64 v[32:33], s[24:25], 2, v[32:33]
	s_lshl_b32 s4, s40, 2
	v_lshl_add_u64 v[32:33], v[32:33], 0, s[4:5]
	global_store_dword v[32:33], v34, off
.LBB0_2679:
	s_or_b64 exec, exec, s[0:1]
	s_waitcnt vmcnt(14)
	v_lshlrev_b32_e32 v34, 16, v108
	v_and_b32_e32 v35, 0xffff0000, v108
	v_lshlrev_b32_e32 v36, 16, v109
	v_and_b32_e32 v37, 0xffff0000, v109
	v_lshlrev_b32_e32 v38, 16, v110
	v_and_b32_e32 v39, 0xffff0000, v110
	v_lshlrev_b32_e32 v40, 16, v111
	v_and_b32_e32 v41, 0xffff0000, v111
	v_pk_add_f32 v[30:31], v[30:31], v[36:37]
	v_pk_add_f32 v[28:29], v[28:29], v[34:35]
	v_pk_add_f32 v[34:35], v[26:27], v[40:41]
	v_pk_add_f32 v[26:27], v[24:25], v[38:39]
	v_mul_f32_e32 v24, v29, v29
	v_mul_f32_e32 v25, v31, v31
	v_fmac_f32_e32 v24, v28, v28
	v_fmac_f32_e32 v25, v30, v30
	v_add_f32_e32 v24, v24, v25
	v_mul_f32_e32 v25, v27, v27
	v_mul_f32_e32 v36, v35, v35
	v_fmac_f32_e32 v25, v26, v26
	v_fmac_f32_e32 v36, v34, v34
	s_waitcnt vmcnt(14)
	v_lshlrev_b32_e32 v42, 16, v104
	v_and_b32_e32 v43, 0xffff0000, v104
	v_lshlrev_b32_e32 v44, 16, v105
	v_and_b32_e32 v45, 0xffff0000, v105
	v_add_f32_e32 v25, v25, v36
	v_lshlrev_b32_e32 v48, 16, v107
	v_and_b32_e32 v49, 0xffff0000, v107
	v_add_f32_e32 v36, v24, v25
	v_cvt_pk_bf16_f32 v24, v28, v29
	v_cvt_pk_bf16_f32 v25, v30, v31
	v_pk_add_f32 v[22:23], v[22:23], v[44:45]
	v_pk_add_f32 v[20:21], v[20:21], v[42:43]
	v_lshlrev_b32_e32 v46, 16, v106
	v_and_b32_e32 v47, 0xffff0000, v106
	v_cvt_pk_bf16_f32 v26, v26, v27
	v_cvt_pk_bf16_f32 v27, v34, v35
	global_store_dwordx4 v[118:119], v[24:27], off sc1 nt
	s_nop 1
	v_pk_add_f32 v[24:25], v[18:19], v[48:49]
	v_mul_f32_e32 v18, v21, v21
	v_mul_f32_e32 v19, v23, v23
	v_pk_add_f32 v[16:17], v[16:17], v[46:47]
	v_fmac_f32_e32 v18, v20, v20
	v_fmac_f32_e32 v19, v22, v22
	v_add_f32_e32 v18, v18, v19
	v_mul_f32_e32 v19, v17, v17
	v_mul_f32_e32 v26, v25, v25
	v_fmac_f32_e32 v19, v16, v16
	v_fmac_f32_e32 v26, v24, v24
	v_add_f32_e32 v19, v19, v26
	v_add_f32_e32 v18, v18, v19
	v_add_f32_e32 v26, v36, v18
	ds_bpermute_b32 v27, v120, v26
	v_cvt_pk_bf16_f32 v18, v20, v21
	v_cvt_pk_bf16_f32 v20, v16, v17
	s_waitcnt lgkmcnt(1)
	v_lshl_add_u64 v[32:33], v[118:119], 0, s[14:15]
	v_cvt_pk_bf16_f32 v19, v22, v23
	s_waitcnt lgkmcnt(0)
	v_add_f32_e32 v16, v26, v27
	ds_bpermute_b32 v17, v121, v16
	v_cvt_pk_bf16_f32 v21, v24, v25
	global_store_dwordx4 v[32:33], v[18:21], off sc1 nt
	s_nop 1
	s_and_saveexec_b64 s[0:1], s[6:7]
	s_cbranch_execz .LBB0_2681
	s_waitcnt lgkmcnt(0)
	v_add_f32_e32 v18, v16, v17
	s_lshl_b32 s24, s45, 2
	v_lshlrev_b64 v[16:17], 6, v[116:117]
	s_ashr_i32 s25, s24, 31
	v_lshl_add_u64 v[16:17], s[16:17], 0, v[16:17]
	v_lshl_add_u64 v[16:17], s[24:25], 2, v[16:17]
	s_lshl_b32 s4, s40, 2
	v_lshl_add_u64 v[16:17], v[16:17], 0, s[4:5]
	global_store_dword v[16:17], v18, off
.LBB0_2681:
	s_or_b64 exec, exec, s[0:1]
	s_waitcnt vmcnt(15)
	v_lshlrev_b32_e32 v18, 16, v100
	v_and_b32_e32 v19, 0xffff0000, v100
	v_lshlrev_b32_e32 v20, 16, v101
	v_and_b32_e32 v21, 0xffff0000, v101
	v_lshlrev_b32_e32 v22, 16, v102
	v_and_b32_e32 v23, 0xffff0000, v102
	v_lshlrev_b32_e32 v24, 16, v103
	v_and_b32_e32 v25, 0xffff0000, v103
	v_pk_add_f32 v[14:15], v[14:15], v[20:21]
	v_pk_add_f32 v[12:13], v[12:13], v[18:19]
	v_pk_add_f32 v[18:19], v[10:11], v[24:25]
	v_pk_add_f32 v[10:11], v[8:9], v[22:23]
	v_mul_f32_e32 v8, v13, v13
	v_mul_f32_e32 v9, v15, v15
	v_fmac_f32_e32 v8, v12, v12
	v_fmac_f32_e32 v9, v14, v14
	v_add_f32_e32 v8, v8, v9
	v_mul_f32_e32 v9, v11, v11
	v_mul_f32_e32 v20, v19, v19
	v_fmac_f32_e32 v9, v10, v10
	v_fmac_f32_e32 v20, v18, v18
	s_waitcnt vmcnt(15)
	v_lshlrev_b32_e32 v26, 16, v96
	v_and_b32_e32 v27, 0xffff0000, v96
	v_lshlrev_b32_e32 v28, 16, v97
	v_and_b32_e32 v29, 0xffff0000, v97
	v_add_f32_e32 v9, v9, v20
	v_lshlrev_b32_e32 v32, 16, v99
	v_and_b32_e32 v33, 0xffff0000, v99
	v_add_f32_e32 v20, v8, v9
	v_cvt_pk_bf16_f32 v8, v12, v13
	v_cvt_pk_bf16_f32 v9, v14, v15
	v_pk_add_f32 v[6:7], v[6:7], v[28:29]
	v_pk_add_f32 v[4:5], v[4:5], v[26:27]
	v_lshlrev_b32_e32 v30, 16, v98
	v_and_b32_e32 v31, 0xffff0000, v98
	v_cvt_pk_bf16_f32 v10, v10, v11
	v_cvt_pk_bf16_f32 v11, v18, v19
	global_store_dwordx4 v[114:115], v[8:11], off sc1 nt
	s_nop 1
	v_pk_add_f32 v[8:9], v[2:3], v[32:33]
	v_mul_f32_e32 v2, v5, v5
	v_mul_f32_e32 v3, v7, v7
	v_pk_add_f32 v[0:1], v[0:1], v[30:31]
	v_fmac_f32_e32 v2, v4, v4
	v_fmac_f32_e32 v3, v6, v6
	v_add_f32_e32 v2, v2, v3
	v_mul_f32_e32 v3, v1, v1
	v_mul_f32_e32 v10, v9, v9
	v_fmac_f32_e32 v3, v0, v0
	v_fmac_f32_e32 v10, v8, v8
	v_add_f32_e32 v3, v3, v10
	v_add_f32_e32 v2, v2, v3
	v_add_f32_e32 v10, v20, v2
	ds_bpermute_b32 v11, v120, v10
	v_cvt_pk_bf16_f32 v2, v4, v5
	v_cvt_pk_bf16_f32 v4, v0, v1
	s_waitcnt lgkmcnt(1)
	v_lshl_add_u64 v[16:17], v[114:115], 0, s[14:15]
	v_cvt_pk_bf16_f32 v3, v6, v7
	s_waitcnt lgkmcnt(0)
	v_add_f32_e32 v0, v10, v11
	ds_bpermute_b32 v1, v121, v0
	v_cvt_pk_bf16_f32 v5, v8, v9
	global_store_dwordx4 v[16:17], v[2:5], off sc1 nt
	s_nop 1
	s_and_saveexec_b64 s[0:1], s[6:7]
	s_cbranch_execz .LBB0_2683
	s_waitcnt lgkmcnt(0)
	v_add_f32_e32 v2, v0, v1
	s_lshl_b32 s24, s45, 2
	v_lshlrev_b64 v[0:1], 6, v[112:113]
	s_ashr_i32 s25, s24, 31
	v_lshl_add_u64 v[0:1], s[16:17], 0, v[0:1]
	v_lshl_add_u64 v[0:1], s[24:25], 2, v[0:1]
	s_lshl_b32 s4, s40, 2
	v_lshl_add_u64 v[0:1], v[0:1], 0, s[4:5]
	global_store_dword v[0:1], v2, off

.LBB0_2877:
	v_lshl_add_u32 v200, s24, 8, v169
	v_lshl_or_b32 v128, s45, 8, v211
	v_ashrrev_i32_e32 v201, 31, v200
	v_lshlrev_b64 v[130:131], 11, v[200:201]
	v_ashrrev_i32_e32 v129, 31, v128
	v_lshl_add_u64 v[130:131], s[12:13], 0, v[130:131]
	v_lshlrev_b64 v[202:203], 1, v[128:129]
	v_lshl_add_u64 v[224:225], v[130:131], 0, v[202:203]
	global_load_dwordx4 v[216:219], v[224:225], off
	global_load_dwordx4 v[220:223], v[224:225], off offset:256
	v_or_b32_e32 v206, 16, v200
	v_or_b32_e32 v198, 32, v200
	v_or_b32_e32 v194, 48, v200
	v_add_u32_e32 v190, 0x80, v200
	v_add_u32_e32 v186, 0x90, v200
	v_ashrrev_i32_e32 v207, 31, v206
	v_ashrrev_i32_e32 v199, 31, v198
	v_ashrrev_i32_e32 v195, 31, v194
	v_ashrrev_i32_e32 v191, 31, v190
	v_ashrrev_i32_e32 v187, 31, v186
	v_lshlrev_b64 v[128:129], 11, v[206:207]
	v_lshlrev_b64 v[130:131], 11, v[198:199]
	v_lshlrev_b64 v[132:133], 11, v[194:195]
	v_lshlrev_b64 v[134:135], 11, v[190:191]
	v_lshlrev_b64 v[136:137], 11, v[186:187]
	v_lshl_add_u64 v[128:129], s[12:13], 0, v[128:129]
	v_lshl_add_u64 v[130:131], s[12:13], 0, v[130:131]
	v_lshl_add_u64 v[132:133], s[12:13], 0, v[132:133]
	v_lshl_add_u64 v[134:135], s[12:13], 0, v[134:135]
	v_lshl_add_u64 v[136:137], s[12:13], 0, v[136:137]
	v_lshl_add_u64 v[208:209], v[128:129], 0, v[202:203]
	v_lshl_add_u64 v[204:205], v[130:131], 0, v[202:203]
	v_lshl_add_u64 v[196:197], v[132:133], 0, v[202:203]
	v_lshl_add_u64 v[192:193], v[134:135], 0, v[202:203]
	v_lshl_add_u64 v[188:189], v[136:137], 0, v[202:203]
	global_load_dwordx4 v[164:167], v[208:209], off
	global_load_dwordx4 v[160:163], v[208:209], off offset:256
	global_load_dwordx4 v[156:159], v[204:205], off
	global_load_dwordx4 v[152:155], v[204:205], off offset:256
	global_load_dwordx4 v[148:151], v[196:197], off
	global_load_dwordx4 v[144:147], v[196:197], off offset:256
	global_load_dwordx4 v[140:143], v[192:193], off
	global_load_dwordx4 v[136:139], v[192:193], off offset:256
	global_load_dwordx4 v[132:135], v[188:189], off
	global_load_dwordx4 v[128:131], v[188:189], off offset:256
	v_lshl_add_u64 v[226:227], v[224:225], 0, s[14:15]
	s_waitcnt vmcnt(8)
	v_lshlrev_b32_e32 v228, 16, v216
	v_and_b32_e32 v229, 0xffff0000, v216
	v_lshlrev_b32_e32 v216, 16, v217
	v_and_b32_e32 v217, 0xffff0000, v217
	v_lshlrev_b32_e32 v230, 16, v218
	v_and_b32_e32 v231, 0xffff0000, v218
	v_lshlrev_b32_e32 v218, 16, v219
	v_and_b32_e32 v219, 0xffff0000, v219
	v_lshlrev_b32_e32 v232, 16, v220
	v_and_b32_e32 v233, 0xffff0000, v220
	v_lshlrev_b32_e32 v220, 16, v221
	v_and_b32_e32 v221, 0xffff0000, v221
	v_lshlrev_b32_e32 v234, 16, v222
	v_and_b32_e32 v235, 0xffff0000, v222
	v_lshlrev_b32_e32 v222, 16, v223
	v_and_b32_e32 v223, 0xffff0000, v223
	v_pk_add_f32 v[126:127], v[126:127], v[216:217]
	v_pk_add_f32 v[124:125], v[124:125], v[228:229]
	v_pk_add_f32 v[122:123], v[122:123], v[218:219]
	v_pk_add_f32 v[120:121], v[120:121], v[230:231]
	v_pk_add_f32 v[118:119], v[118:119], v[220:221]
	v_pk_add_f32 v[216:217], v[114:115], v[222:223]
	v_mul_f32_e32 v220, v125, v125
	v_mul_f32_e32 v221, v127, v127
	v_mul_f32_e32 v222, v121, v121
	v_mul_f32_e32 v223, v123, v123
	v_pk_add_f32 v[218:219], v[112:113], v[234:235]
	v_cvt_pk_bf16_f32 v112, v124, v125
	v_cvt_pk_bf16_f32 v113, v126, v127
	v_fmac_f32_e32 v220, v124, v124
	v_fmac_f32_e32 v221, v126, v126
	v_fmac_f32_e32 v222, v120, v120
	v_fmac_f32_e32 v223, v122, v122
	v_pk_add_f32 v[116:117], v[116:117], v[232:233]
	v_cvt_pk_bf16_f32 v114, v120, v121
	v_cvt_pk_bf16_f32 v115, v122, v123
	global_store_dwordx4 v[224:225], v[112:115], off sc1 nt
	s_nop 1
	v_add_f32_e32 v112, v220, v221
	v_add_f32_e32 v113, v222, v223
	v_mul_f32_e32 v121, v117, v117
	v_mul_f32_e32 v123, v119, v119
	v_add_f32_e32 v112, v112, v113
	v_mul_f32_e32 v113, v219, v219
	v_mul_f32_e32 v115, v217, v217
	v_fmac_f32_e32 v121, v116, v116
	v_fmac_f32_e32 v123, v118, v118
	v_fmac_f32_e32 v113, v218, v218
	v_fmac_f32_e32 v115, v216, v216
	v_add_f32_e32 v114, v121, v123
	v_add_f32_e32 v113, v113, v115
	v_add_f32_e32 v113, v114, v113
	v_and_b32_e32 v114, 64, v215
	v_add_f32_e32 v112, v112, v113
	v_xor_b32_e32 v113, 16, v215
	v_add_u32_e32 v121, 64, v114
	v_cmp_lt_i32_e32 vcc, v113, v121
	v_cvt_pk_bf16_f32 v114, v116, v117
	v_cvt_pk_bf16_f32 v115, v118, v119
	v_cndmask_b32_e32 v113, v215, v113, vcc
	v_lshlrev_b32_e32 v120, 2, v113
	ds_bpermute_b32 v113, v120, v112
	v_cvt_pk_bf16_f32 v116, v218, v219
	v_cvt_pk_bf16_f32 v117, v216, v217
	global_store_dwordx4 v[226:227], v[114:117], off sc1 nt
	s_nop 1
	s_waitcnt lgkmcnt(0)
	v_add_f32_e32 v112, v112, v113
	v_xor_b32_e32 v113, 32, v215
	v_cmp_lt_i32_e32 vcc, v113, v121
	s_nop 1
	v_cndmask_b32_e32 v113, v215, v113, vcc
	v_lshlrev_b32_e32 v121, 2, v113
	ds_bpermute_b32 v113, v121, v112
	s_and_saveexec_b64 s[0:1], s[6:7]
	s_cbranch_execz .LBB0_2879
	s_waitcnt lgkmcnt(0)
	v_add_f32_e32 v114, v112, v113
	s_lshl_b32 s24, s45, 2
	v_lshlrev_b64 v[112:113], 6, v[200:201]
	s_ashr_i32 s25, s24, 31
	v_lshl_add_u64 v[112:113], s[16:17], 0, v[112:113]
	v_lshl_add_u64 v[112:113], s[24:25], 2, v[112:113]
	s_lshl_b32 s4, s40, 2
	v_lshl_add_u64 v[112:113], v[112:113], 0, s[4:5]
	global_store_dword v[112:113], v114, off
.LBB0_2879:
	s_or_b64 exec, exec, s[0:1]
	v_lshlrev_b32_e32 v114, 16, v164
	v_and_b32_e32 v115, 0xffff0000, v164
	v_lshlrev_b32_e32 v116, 16, v165
	v_and_b32_e32 v117, 0xffff0000, v165
	v_lshlrev_b32_e32 v118, 16, v166
	v_and_b32_e32 v119, 0xffff0000, v166
	v_lshlrev_b32_e32 v122, 16, v167
	v_and_b32_e32 v123, 0xffff0000, v167
	v_pk_add_f32 v[110:111], v[110:111], v[116:117]
	v_pk_add_f32 v[108:109], v[108:109], v[114:115]
	v_pk_add_f32 v[114:115], v[106:107], v[122:123]
	v_pk_add_f32 v[106:107], v[104:105], v[118:119]
	v_mul_f32_e32 v104, v109, v109
	v_mul_f32_e32 v105, v111, v111
	v_fmac_f32_e32 v104, v108, v108
	v_fmac_f32_e32 v105, v110, v110
	v_add_f32_e32 v104, v104, v105
	v_mul_f32_e32 v105, v107, v107
	v_mul_f32_e32 v116, v115, v115
	v_fmac_f32_e32 v105, v106, v106
	v_fmac_f32_e32 v116, v114, v114
	v_lshlrev_b32_e32 v124, 16, v160
	v_and_b32_e32 v125, 0xffff0000, v160
	v_lshlrev_b32_e32 v126, 16, v161
	v_and_b32_e32 v127, 0xffff0000, v161
	v_add_f32_e32 v105, v105, v116
	v_lshlrev_b32_e32 v160, 16, v162
	v_and_b32_e32 v161, 0xffff0000, v162
	v_lshlrev_b32_e32 v162, 16, v163
	v_and_b32_e32 v163, 0xffff0000, v163
	v_add_f32_e32 v116, v104, v105
	v_cvt_pk_bf16_f32 v104, v108, v109
	v_cvt_pk_bf16_f32 v105, v110, v111
	v_pk_add_f32 v[102:103], v[102:103], v[126:127]
	v_pk_add_f32 v[100:101], v[100:101], v[124:125]
	v_cvt_pk_bf16_f32 v106, v106, v107
	v_cvt_pk_bf16_f32 v107, v114, v115
	global_store_dwordx4 v[208:209], v[104:107], off sc1 nt
	s_nop 1
	v_pk_add_f32 v[104:105], v[98:99], v[162:163]
	v_mul_f32_e32 v98, v101, v101
	v_mul_f32_e32 v99, v103, v103
	v_pk_add_f32 v[96:97], v[96:97], v[160:161]
	v_fmac_f32_e32 v98, v100, v100
	v_fmac_f32_e32 v99, v102, v102
	v_add_f32_e32 v98, v98, v99
	v_mul_f32_e32 v99, v97, v97
	v_mul_f32_e32 v106, v105, v105
	v_fmac_f32_e32 v99, v96, v96
	v_fmac_f32_e32 v106, v104, v104
	v_add_f32_e32 v99, v99, v106
	v_add_f32_e32 v98, v98, v99
	v_add_f32_e32 v106, v116, v98
	ds_bpermute_b32 v107, v120, v106
	v_cvt_pk_bf16_f32 v98, v100, v101
	v_cvt_pk_bf16_f32 v100, v96, v97
	s_waitcnt lgkmcnt(1)
	v_lshl_add_u64 v[112:113], v[208:209], 0, s[14:15]
	v_cvt_pk_bf16_f32 v99, v102, v103
	s_waitcnt lgkmcnt(0)
	v_add_f32_e32 v96, v106, v107
	ds_bpermute_b32 v97, v121, v96
	v_cvt_pk_bf16_f32 v101, v104, v105
	global_store_dwordx4 v[112:113], v[98:101], off sc1 nt
	s_nop 1
	s_and_saveexec_b64 s[0:1], s[6:7]
	s_cbranch_execz .LBB0_2881
	s_waitcnt lgkmcnt(0)
	v_add_f32_e32 v98, v96, v97
	s_lshl_b32 s24, s45, 2
	v_lshlrev_b64 v[96:97], 6, v[206:207]
	s_ashr_i32 s25, s24, 31
	v_lshl_add_u64 v[96:97], s[16:17], 0, v[96:97]
	v_lshl_add_u64 v[96:97], s[24:25], 2, v[96:97]
	s_lshl_b32 s4, s40, 2
	v_lshl_add_u64 v[96:97], v[96:97], 0, s[4:5]
	global_store_dword v[96:97], v98, off
.LBB0_2881:
	s_or_b64 exec, exec, s[0:1]
	v_add_u32_e32 v116, 0xa0, v200
	v_ashrrev_i32_e32 v117, 31, v116
	s_waitcnt lgkmcnt(0)
	v_lshlrev_b64 v[96:97], 11, v[116:117]
	v_add_u32_e32 v112, 0xb0, v200
	v_lshl_add_u64 v[96:97], s[12:13], 0, v[96:97]
	v_ashrrev_i32_e32 v113, 31, v112
	v_lshl_add_u64 v[118:119], v[96:97], 0, v[202:203]
	v_lshlrev_b64 v[96:97], 11, v[112:113]
	v_lshl_add_u64 v[96:97], s[12:13], 0, v[96:97]
	v_lshl_add_u64 v[114:115], v[96:97], 0, v[202:203]
	global_load_dwordx4 v[108:111], v[118:119], off
	global_load_dwordx4 v[104:107], v[118:119], off offset:256
	global_load_dwordx4 v[100:103], v[114:115], off
	global_load_dwordx4 v[96:99], v[114:115], off offset:256
	s_waitcnt vmcnt(14)
	v_lshlrev_b32_e32 v124, 16, v156
	v_and_b32_e32 v125, 0xffff0000, v156
	v_lshlrev_b32_e32 v126, 16, v157
	v_and_b32_e32 v127, 0xffff0000, v157
	v_lshlrev_b32_e32 v156, 16, v158
	v_and_b32_e32 v157, 0xffff0000, v158
	v_lshlrev_b32_e32 v158, 16, v159
	v_and_b32_e32 v159, 0xffff0000, v159
	v_pk_add_f32 v[94:95], v[94:95], v[126:127]
	v_pk_add_f32 v[92:93], v[92:93], v[124:125]
	v_pk_add_f32 v[124:125], v[90:91], v[158:159]
	v_pk_add_f32 v[90:91], v[88:89], v[156:157]
	v_mul_f32_e32 v88, v93, v93
	v_mul_f32_e32 v89, v95, v95
	v_fmac_f32_e32 v88, v92, v92
	v_fmac_f32_e32 v89, v94, v94
	v_add_f32_e32 v88, v88, v89
	v_mul_f32_e32 v89, v91, v91
	v_mul_f32_e32 v126, v125, v125
	v_fmac_f32_e32 v89, v90, v90
	v_fmac_f32_e32 v126, v124, v124
	v_lshlrev_b32_e32 v160, 16, v152
	v_and_b32_e32 v161, 0xffff0000, v152
	v_lshlrev_b32_e32 v152, 16, v153
	v_and_b32_e32 v153, 0xffff0000, v153
	v_add_f32_e32 v89, v89, v126
	v_lshlrev_b32_e32 v162, 16, v154
	v_and_b32_e32 v163, 0xffff0000, v154
	v_lshlrev_b32_e32 v154, 16, v155
	v_and_b32_e32 v155, 0xffff0000, v155
	v_add_f32_e32 v126, v88, v89
	v_cvt_pk_bf16_f32 v88, v92, v93
	v_cvt_pk_bf16_f32 v89, v94, v95
	v_pk_add_f32 v[86:87], v[86:87], v[152:153]
	v_pk_add_f32 v[84:85], v[84:85], v[160:161]
	v_cvt_pk_bf16_f32 v90, v90, v91
	v_cvt_pk_bf16_f32 v91, v124, v125
	global_store_dwordx4 v[204:205], v[88:91], off sc1 nt
	s_nop 1
	v_pk_add_f32 v[88:89], v[82:83], v[154:155]
	v_mul_f32_e32 v82, v85, v85
	v_mul_f32_e32 v83, v87, v87
	v_pk_add_f32 v[80:81], v[80:81], v[162:163]
	v_fmac_f32_e32 v82, v84, v84
	v_fmac_f32_e32 v83, v86, v86
	v_add_f32_e32 v82, v82, v83
	v_mul_f32_e32 v83, v81, v81
	v_mul_f32_e32 v90, v89, v89
	v_fmac_f32_e32 v83, v80, v80
	v_fmac_f32_e32 v90, v88, v88
	v_add_f32_e32 v83, v83, v90
	v_add_f32_e32 v82, v82, v83
	v_add_f32_e32 v90, v126, v82
	ds_bpermute_b32 v91, v120, v90
	v_cvt_pk_bf16_f32 v82, v84, v85
	v_cvt_pk_bf16_f32 v84, v80, v81
	v_lshl_add_u64 v[122:123], v[204:205], 0, s[14:15]
	v_cvt_pk_bf16_f32 v83, v86, v87
	s_waitcnt lgkmcnt(0)
	v_add_f32_e32 v80, v90, v91
	ds_bpermute_b32 v81, v121, v80
	v_cvt_pk_bf16_f32 v85, v88, v89
	global_store_dwordx4 v[122:123], v[82:85], off sc1 nt
	s_nop 1
	s_and_saveexec_b64 s[0:1], s[6:7]
	s_cbranch_execz .LBB0_2883
	s_waitcnt lgkmcnt(0)
	v_add_f32_e32 v82, v80, v81
	s_lshl_b32 s24, s45, 2
	v_lshlrev_b64 v[80:81], 6, v[198:199]
	s_ashr_i32 s25, s24, 31
	v_lshl_add_u64 v[80:81], s[16:17], 0, v[80:81]
	v_lshl_add_u64 v[80:81], s[24:25], 2, v[80:81]
	s_lshl_b32 s4, s40, 2
	v_lshl_add_u64 v[80:81], v[80:81], 0, s[4:5]
	global_store_dword v[80:81], v82, off
.LBB0_2883:
	s_or_b64 exec, exec, s[0:1]
	v_lshlrev_b32_e32 v82, 16, v148
	v_and_b32_e32 v83, 0xffff0000, v148
	v_lshlrev_b32_e32 v84, 16, v149
	v_and_b32_e32 v85, 0xffff0000, v149
	v_lshlrev_b32_e32 v86, 16, v150
	v_and_b32_e32 v87, 0xffff0000, v150
	v_lshlrev_b32_e32 v88, 16, v151
	v_and_b32_e32 v89, 0xffff0000, v151
	v_pk_add_f32 v[78:79], v[78:79], v[84:85]
	v_pk_add_f32 v[76:77], v[76:77], v[82:83]
	v_pk_add_f32 v[82:83], v[74:75], v[88:89]
	v_pk_add_f32 v[74:75], v[72:73], v[86:87]
	v_mul_f32_e32 v72, v77, v77
	v_mul_f32_e32 v73, v79, v79
	v_fmac_f32_e32 v72, v76, v76
	v_fmac_f32_e32 v73, v78, v78
	v_add_f32_e32 v72, v72, v73
	v_mul_f32_e32 v73, v75, v75
	v_mul_f32_e32 v84, v83, v83
	v_fmac_f32_e32 v73, v74, v74
	v_fmac_f32_e32 v84, v82, v82
	v_lshlrev_b32_e32 v90, 16, v144
	v_and_b32_e32 v91, 0xffff0000, v144
	v_lshlrev_b32_e32 v92, 16, v145
	v_and_b32_e32 v93, 0xffff0000, v145
	v_add_f32_e32 v73, v73, v84
	v_lshlrev_b32_e32 v122, 16, v147
	v_and_b32_e32 v123, 0xffff0000, v147
	v_add_f32_e32 v84, v72, v73
	v_cvt_pk_bf16_f32 v72, v76, v77
	v_cvt_pk_bf16_f32 v73, v78, v79
	v_pk_add_f32 v[70:71], v[70:71], v[92:93]
	v_pk_add_f32 v[68:69], v[68:69], v[90:91]
	v_lshlrev_b32_e32 v94, 16, v146
	v_and_b32_e32 v95, 0xffff0000, v146
	v_cvt_pk_bf16_f32 v74, v74, v75
	v_cvt_pk_bf16_f32 v75, v82, v83
	global_store_dwordx4 v[196:197], v[72:75], off sc1 nt
	s_nop 1
	v_pk_add_f32 v[72:73], v[66:67], v[122:123]
	v_mul_f32_e32 v66, v69, v69
	v_mul_f32_e32 v67, v71, v71
	v_pk_add_f32 v[64:65], v[64:65], v[94:95]
	v_fmac_f32_e32 v66, v68, v68
	v_fmac_f32_e32 v67, v70, v70
	v_add_f32_e32 v66, v66, v67
	v_mul_f32_e32 v67, v65, v65
	v_mul_f32_e32 v74, v73, v73
	v_fmac_f32_e32 v67, v64, v64
	v_fmac_f32_e32 v74, v72, v72
	v_add_f32_e32 v67, v67, v74
	v_add_f32_e32 v66, v66, v67
	v_add_f32_e32 v74, v84, v66
	ds_bpermute_b32 v75, v120, v74
	v_cvt_pk_bf16_f32 v66, v68, v69
	v_cvt_pk_bf16_f32 v68, v64, v65
	s_waitcnt lgkmcnt(1)
	v_lshl_add_u64 v[80:81], v[196:197], 0, s[14:15]
	v_cvt_pk_bf16_f32 v67, v70, v71
	s_waitcnt lgkmcnt(0)
	v_add_f32_e32 v64, v74, v75
	ds_bpermute_b32 v65, v121, v64
	v_cvt_pk_bf16_f32 v69, v72, v73
	global_store_dwordx4 v[80:81], v[66:69], off sc1 nt
	s_nop 1
	s_and_saveexec_b64 s[0:1], s[6:7]
	s_cbranch_execz .LBB0_2885
	s_waitcnt lgkmcnt(0)
	v_add_f32_e32 v66, v64, v65
	s_lshl_b32 s24, s45, 2
	v_lshlrev_b64 v[64:65], 6, v[194:195]
	s_ashr_i32 s25, s24, 31
	v_lshl_add_u64 v[64:65], s[16:17], 0, v[64:65]
	v_lshl_add_u64 v[64:65], s[24:25], 2, v[64:65]
	s_lshl_b32 s4, s40, 2
	v_lshl_add_u64 v[64:65], v[64:65], 0, s[4:5]
	global_store_dword v[64:65], v66, off
.LBB0_2885:
	s_or_b64 exec, exec, s[0:1]
	s_waitcnt vmcnt(16)
	v_lshlrev_b32_e32 v66, 16, v140
	v_and_b32_e32 v67, 0xffff0000, v140
	v_lshlrev_b32_e32 v68, 16, v141
	v_and_b32_e32 v69, 0xffff0000, v141
	v_lshlrev_b32_e32 v70, 16, v142
	v_and_b32_e32 v71, 0xffff0000, v142
	v_lshlrev_b32_e32 v72, 16, v143
	v_and_b32_e32 v73, 0xffff0000, v143
	v_pk_add_f32 v[62:63], v[62:63], v[68:69]
	v_pk_add_f32 v[60:61], v[60:61], v[66:67]
	v_pk_add_f32 v[66:67], v[58:59], v[72:73]
	v_pk_add_f32 v[58:59], v[56:57], v[70:71]
	v_mul_f32_e32 v56, v61, v61
	v_mul_f32_e32 v57, v63, v63
	v_fmac_f32_e32 v56, v60, v60
	v_fmac_f32_e32 v57, v62, v62
	v_add_f32_e32 v56, v56, v57
	v_mul_f32_e32 v57, v59, v59
	v_mul_f32_e32 v68, v67, v67
	v_fmac_f32_e32 v57, v58, v58
	v_fmac_f32_e32 v68, v66, v66
	v_lshlrev_b32_e32 v74, 16, v136
	v_and_b32_e32 v75, 0xffff0000, v136
	v_lshlrev_b32_e32 v76, 16, v137
	v_and_b32_e32 v77, 0xffff0000, v137
	v_add_f32_e32 v57, v57, v68
	v_lshlrev_b32_e32 v80, 16, v139
	v_and_b32_e32 v81, 0xffff0000, v139
	v_add_f32_e32 v68, v56, v57
	v_cvt_pk_bf16_f32 v56, v60, v61
	v_cvt_pk_bf16_f32 v57, v62, v63
	v_pk_add_f32 v[54:55], v[54:55], v[76:77]
	v_pk_add_f32 v[52:53], v[52:53], v[74:75]
	v_lshlrev_b32_e32 v78, 16, v138
	v_and_b32_e32 v79, 0xffff0000, v138
	v_cvt_pk_bf16_f32 v58, v58, v59
	v_cvt_pk_bf16_f32 v59, v66, v67
	global_store_dwordx4 v[192:193], v[56:59], off sc1 nt
	s_nop 1
	v_pk_add_f32 v[56:57], v[50:51], v[80:81]
	v_mul_f32_e32 v50, v53, v53
	v_mul_f32_e32 v51, v55, v55
	v_pk_add_f32 v[48:49], v[48:49], v[78:79]
	v_fmac_f32_e32 v50, v52, v52
	v_fmac_f32_e32 v51, v54, v54
	v_add_f32_e32 v50, v50, v51
	v_mul_f32_e32 v51, v49, v49
	v_mul_f32_e32 v58, v57, v57
	v_fmac_f32_e32 v51, v48, v48
	v_fmac_f32_e32 v58, v56, v56
	v_add_f32_e32 v51, v51, v58
	v_add_f32_e32 v50, v50, v51
	v_add_f32_e32 v58, v68, v50
	ds_bpermute_b32 v59, v120, v58
	v_cvt_pk_bf16_f32 v50, v52, v53
	v_cvt_pk_bf16_f32 v52, v48, v49
	s_waitcnt lgkmcnt(1)
	v_lshl_add_u64 v[64:65], v[192:193], 0, s[14:15]
	v_cvt_pk_bf16_f32 v51, v54, v55
	s_waitcnt lgkmcnt(0)
	v_add_f32_e32 v48, v58, v59
	ds_bpermute_b32 v49, v121, v48
	v_cvt_pk_bf16_f32 v53, v56, v57
	global_store_dwordx4 v[64:65], v[50:53], off sc1 nt
	s_nop 1
	s_and_saveexec_b64 s[0:1], s[6:7]
	s_cbranch_execz .LBB0_2887
	s_waitcnt lgkmcnt(0)
	v_add_f32_e32 v50, v48, v49
	s_lshl_b32 s24, s45, 2
	v_lshlrev_b64 v[48:49], 6, v[190:191]
	s_ashr_i32 s25, s24, 31
	v_lshl_add_u64 v[48:49], s[16:17], 0, v[48:49]
	v_lshl_add_u64 v[48:49], s[24:25], 2, v[48:49]
	s_lshl_b32 s4, s40, 2
	v_lshl_add_u64 v[48:49], v[48:49], 0, s[4:5]
	global_store_dword v[48:49], v50, off
.LBB0_2887:
	s_or_b64 exec, exec, s[0:1]
	v_lshlrev_b32_e32 v50, 16, v132
	v_and_b32_e32 v51, 0xffff0000, v132
	v_lshlrev_b32_e32 v52, 16, v133
	v_and_b32_e32 v53, 0xffff0000, v133
	v_lshlrev_b32_e32 v54, 16, v134
	v_and_b32_e32 v55, 0xffff0000, v134
	v_lshlrev_b32_e32 v56, 16, v135
	v_and_b32_e32 v57, 0xffff0000, v135
	v_pk_add_f32 v[46:47], v[46:47], v[52:53]
	v_pk_add_f32 v[44:45], v[44:45], v[50:51]
	v_pk_add_f32 v[50:51], v[42:43], v[56:57]
	v_pk_add_f32 v[42:43], v[40:41], v[54:55]
	v_mul_f32_e32 v40, v45, v45
	v_mul_f32_e32 v41, v47, v47
	v_fmac_f32_e32 v40, v44, v44
	v_fmac_f32_e32 v41, v46, v46
	v_add_f32_e32 v40, v40, v41
	v_mul_f32_e32 v41, v43, v43
	v_mul_f32_e32 v52, v51, v51
	v_fmac_f32_e32 v41, v42, v42
	v_fmac_f32_e32 v52, v50, v50
	v_lshlrev_b32_e32 v58, 16, v128
	v_and_b32_e32 v59, 0xffff0000, v128
	v_lshlrev_b32_e32 v60, 16, v129
	v_and_b32_e32 v61, 0xffff0000, v129
	v_add_f32_e32 v41, v41, v52
	v_lshlrev_b32_e32 v64, 16, v131
	v_and_b32_e32 v65, 0xffff0000, v131
	v_add_f32_e32 v52, v40, v41
	v_cvt_pk_bf16_f32 v40, v44, v45
	v_cvt_pk_bf16_f32 v41, v46, v47
	v_pk_add_f32 v[38:39], v[38:39], v[60:61]
	v_pk_add_f32 v[36:37], v[36:37], v[58:59]
	v_lshlrev_b32_e32 v62, 16, v130
	v_and_b32_e32 v63, 0xffff0000, v130
	v_cvt_pk_bf16_f32 v42, v42, v43
	v_cvt_pk_bf16_f32 v43, v50, v51
	global_store_dwordx4 v[188:189], v[40:43], off sc1 nt
	s_nop 1
	v_pk_add_f32 v[40:41], v[34:35], v[64:65]
	v_mul_f32_e32 v34, v37, v37
	v_mul_f32_e32 v35, v39, v39
	v_pk_add_f32 v[32:33], v[32:33], v[62:63]
	v_fmac_f32_e32 v34, v36, v36
	v_fmac_f32_e32 v35, v38, v38
	v_add_f32_e32 v34, v34, v35
	v_mul_f32_e32 v35, v33, v33
	v_mul_f32_e32 v42, v41, v41
	v_fmac_f32_e32 v35, v32, v32
	v_fmac_f32_e32 v42, v40, v40
	v_add_f32_e32 v35, v35, v42
	v_add_f32_e32 v34, v34, v35
	v_add_f32_e32 v42, v52, v34
	ds_bpermute_b32 v43, v120, v42
	v_cvt_pk_bf16_f32 v34, v36, v37
	v_cvt_pk_bf16_f32 v36, v32, v33
	s_waitcnt lgkmcnt(1)
	v_lshl_add_u64 v[48:49], v[188:189], 0, s[14:15]
	v_cvt_pk_bf16_f32 v35, v38, v39
	s_waitcnt lgkmcnt(0)
	v_add_f32_e32 v32, v42, v43
	ds_bpermute_b32 v33, v121, v32
	v_cvt_pk_bf16_f32 v37, v40, v41
	global_store_dwordx4 v[48:49], v[34:37], off sc1 nt
	s_nop 1
	s_and_saveexec_b64 s[0:1], s[6:7]
	s_cbranch_execz .LBB0_2889
	s_waitcnt lgkmcnt(0)
	v_add_f32_e32 v34, v32, v33
	s_lshl_b32 s24, s45, 2
	v_lshlrev_b64 v[32:33], 6, v[186:187]
	s_ashr_i32 s25, s24, 31
	v_lshl_add_u64 v[32:33], s[16:17], 0, v[32:33]
	v_lshl_add_u64 v[32:33], s[24:25], 2, v[32:33]
	s_lshl_b32 s4, s40, 2
	v_lshl_add_u64 v[32:33], v[32:33], 0, s[4:5]
	global_store_dword v[32:33], v34, off
